# stick-breaking units: fmaxf operand canonicalisation (v_max x,x) folded into the following max(0,x): 32 fewer VALU per 64-key tile
# baseline (speedup 1.0000x reference)
; template <bool NEED_SUM>
; __device__ __forceinline__ void sb_part1(SbTile& t, float& tsum, lds_cptr kslot, const bf16x8 (&qr)[4], bool masked, int qlim, int r32, int hi) {
;     bf16x8 kf[8]; kfrags(kf, kslot, r32, hi);
;     t.z0 = (f32x16){}; t.z1 = (f32x16){};
; #pragma unroll
;     for (int d0 = 0; d0 < 4; ++d0) {
;         t.z0 = __builtin_amdgcn_mfma_f32_32x32x16_bf16(kf[2 * d0], qr[d0], t.z0, 0, 0, 0);
;         t.z1 = __builtin_amdgcn_mfma_f32_32x32x16_bf16(kf[2 * d0 + 1], qr[d0], t.z1, 0, 0, 0);
;     }
;     __builtin_amdgcn_sched_barrier(0);
;     f32x16 l0, l1;
; #pragma unroll
;     for (int r = 0; r < 16; ++r) {
;         const float a0 = t.z0[r], a1 = t.z1[r];
;         l0[r] = fmaxf(a0, 0.f) + __builtin_amdgcn_logf(1.0f + __builtin_amdgcn_exp2f(-__builtin_fabsf(a0)));
;         l1[r] = fmaxf(a1, 0.f) + __builtin_amdgcn_logf(1.0f + __builtin_amdgcn_exp2f(-__builtin_fabsf(a1)));
;     }
.LBB0_286:
	s_add_i32 s80, s95, s3
	s_cmp_lt_i32 s80, 0
	s_cselect_b64 s[90:91], -1, 0
	s_or_b64 s[90:91], s[90:91], s[74:75]
	s_and_b64 vcc, exec, s[90:91]
	s_cbranch_vccnz .LBB0_292
	s_add_i32 s74, s93, s94
	s_add_i32 s74, s74, 0x8000
	s_and_b32 s81, s74, 0xe000
	v_add_u32_e32 v2, s81, v172
	ds_read_b128 v[6:9], v2
	s_waitcnt lgkmcnt(0)
	v_mfma_f32_32x32x16_bf16 v[68:83], v[6:9], v[124:127], 0
	ds_read_b128 v[6:9], v2 offset:512
	s_waitcnt lgkmcnt(0)
	v_mfma_f32_32x32x16_bf16 v[84:99], v[6:9], v[124:127], 0
	ds_read_b128 v[6:9], v2 offset:2048
	s_waitcnt lgkmcnt(0)
	v_mfma_f32_32x32x16_bf16 v[68:83], v[6:9], v[128:131], v[68:83]
	ds_read_b128 v[6:9], v2 offset:2560
	s_waitcnt lgkmcnt(0)
	v_mfma_f32_32x32x16_bf16 v[84:99], v[6:9], v[128:131], v[84:99]
	ds_read_b128 v[6:9], v2 offset:4096
	s_waitcnt lgkmcnt(0)
	v_mfma_f32_32x32x16_bf16 v[68:83], v[6:9], v[132:135], v[68:83]
	ds_read_b128 v[6:9], v2 offset:4608
	s_waitcnt lgkmcnt(0)
	v_mfma_f32_32x32x16_bf16 v[84:99], v[6:9], v[132:135], v[84:99]
	ds_read_b128 v[6:9], v2 offset:6144
	s_waitcnt lgkmcnt(0)
	v_mfma_f32_32x32x16_bf16 v[68:83], v[6:9], v[136:139], v[68:83]
	ds_read_b128 v[6:9], v2 offset:6656
	s_waitcnt lgkmcnt(0)
	v_mfma_f32_32x32x16_bf16 v[84:99], v[6:9], v[136:139], v[84:99]
	s_nop 8
	v_exp_f32_e64 v3, -|v68|
	s_nop 1
	v_exp_f32_e64 v4, -|v84|
	v_exp_f32_e64 v8, -|v85|
	v_exp_f32_e64 v9, -|v70|
	v_add_f32_e32 v3, 1.0, v3
	v_log_f32_e32 v6, v3
	v_max_f32_e32 v12, 0, v84
	v_add_f32_e32 v3, 1.0, v4
	v_exp_f32_e64 v4, -|v69|
	v_exp_f32_e64 v11, -|v71|
	v_exp_f32_e64 v53, -|v87|
	v_log_f32_e32 v14, v3
	v_add_f32_e32 v4, 1.0, v4
	v_log_f32_e32 v7, v4
	v_max_f32_e32 v13, 0, v85
	v_add_f32_e32 v4, 1.0, v8
	v_log_f32_e32 v15, v4
	v_max_f32_e32 v8, 0, v70
	v_add_f32_e32 v4, 1.0, v9
	v_exp_f32_e64 v9, -|v86|
	v_log_f32_e32 v10, v4
	v_max_f32_e32 v16, 0, v86
	v_add_f32_e32 v4, 1.0, v9
	v_log_f32_e32 v54, v4
	v_max_f32_e32 v9, 0, v71
	v_add_f32_e32 v4, 1.0, v11
	v_log_f32_e32 v11, v4
	v_max_f32_e32 v17, 0, v87
	v_add_f32_e32 v4, 1.0, v53
	v_exp_f32_e64 v53, -|v72|
	v_log_f32_e32 v55, v4
	v_max_f32_e32 v60, 0, v72
	v_add_f32_e32 v4, 1.0, v53
	v_exp_f32_e64 v53, -|v88|
	v_log_f32_e32 v62, v4
	v_max_f32_e32 v64, 0, v88
	v_add_f32_e32 v4, 1.0, v53
	v_exp_f32_e64 v53, -|v73|
	v_log_f32_e32 v66, v4
	v_max_f32_e32 v61, 0, v73
	v_add_f32_e32 v4, 1.0, v53
	v_exp_f32_e64 v53, -|v89|
	v_log_f32_e32 v63, v4
	v_max_f32_e32 v65, 0, v89
	v_add_f32_e32 v4, 1.0, v53
	v_exp_f32_e64 v53, -|v74|
	v_log_f32_e32 v67, v4
	v_max_f32_e32 v100, 0, v74
	v_add_f32_e32 v4, 1.0, v53
	v_exp_f32_e64 v53, -|v90|
	v_log_f32_e32 v102, v4
	v_max_f32_e32 v104, 0, v90
	v_add_f32_e32 v4, 1.0, v53
	v_exp_f32_e64 v53, -|v75|
	v_log_f32_e32 v106, v4
	v_max_f32_e32 v101, 0, v75
	v_add_f32_e32 v4, 1.0, v53
	v_exp_f32_e64 v53, -|v91|
	v_log_f32_e32 v103, v4
	v_max_f32_e32 v105, 0, v91
	v_add_f32_e32 v4, 1.0, v53
	v_exp_f32_e64 v53, -|v76|
	v_log_f32_e32 v107, v4
	v_max_f32_e32 v108, 0, v76
	v_add_f32_e32 v4, 1.0, v53
	v_exp_f32_e64 v53, -|v92|
	v_log_f32_e32 v110, v4
	v_max_f32_e32 v112, 0, v92
	v_add_f32_e32 v4, 1.0, v53
	v_exp_f32_e64 v53, -|v77|
	v_log_f32_e32 v114, v4
	v_max_f32_e32 v109, 0, v77
	v_add_f32_e32 v4, 1.0, v53
	v_exp_f32_e64 v53, -|v93|
	v_log_f32_e32 v111, v4
	v_max_f32_e32 v113, 0, v93
	v_add_f32_e32 v4, 1.0, v53
	v_exp_f32_e64 v53, -|v78|
	v_log_f32_e32 v115, v4
	v_max_f32_e32 v140, 0, v78
	v_add_f32_e32 v4, 1.0, v53
	v_exp_f32_e64 v53, -|v94|
	v_log_f32_e32 v142, v4
	v_max_f32_e32 v148, 0, v94
	v_add_f32_e32 v4, 1.0, v53
	v_exp_f32_e64 v53, -|v79|
	v_log_f32_e32 v150, v4
	v_max_f32_e32 v141, 0, v79
	v_add_f32_e32 v4, 1.0, v53
	v_exp_f32_e64 v53, -|v95|
	v_log_f32_e32 v143, v4
	v_max_f32_e32 v149, 0, v95
	v_add_f32_e32 v4, 1.0, v53
	v_exp_f32_e64 v53, -|v80|
	v_log_f32_e32 v151, v4
	v_max_f32_e32 v144, 0, v80
	v_add_f32_e32 v4, 1.0, v53
	v_exp_f32_e64 v53, -|v96|
	v_log_f32_e32 v146, v4
	v_max_f32_e32 v152, 0, v96
	v_add_f32_e32 v4, 1.0, v53
	v_exp_f32_e64 v53, -|v81|
	v_log_f32_e32 v154, v4
	v_max_f32_e32 v145, 0, v81
	v_add_f32_e32 v4, 1.0, v53
	v_exp_f32_e64 v53, -|v97|
	v_log_f32_e32 v147, v4
	v_max_f32_e32 v153, 0, v97
	v_add_f32_e32 v4, 1.0, v53
	v_exp_f32_e64 v53, -|v82|
	v_log_f32_e32 v155, v4
	v_max_f32_e32 v156, 0, v82
	v_add_f32_e32 v4, 1.0, v53
	v_exp_f32_e64 v53, -|v98|
	v_log_f32_e32 v158, v4
	v_max_f32_e32 v174, 0, v98
	v_add_f32_e32 v4, 1.0, v53
	v_exp_f32_e64 v53, -|v83|
	v_log_f32_e32 v176, v4
	v_max_f32_e32 v157, 0, v83
	v_add_f32_e32 v4, 1.0, v53
	v_log_f32_e32 v159, v4
	v_exp_f32_e64 v4, -|v99|
	v_max_f32_e32 v53, v99, v99
	v_add_f32_e32 v4, 1.0, v4
	v_log_f32_e32 v177, v4
	v_max_f32_e32 v2, 0, v68
	v_max_f32_e32 v3, 0, v69
	v_max_f32_e32 v175, 0, v53
	v_cndmask_b32_e64 v4, 0, 1, s[4:5]
	v_pk_add_f32 v[56:57], v[2:3], v[6:7]
	v_pk_add_f32 v[58:59], v[8:9], v[10:11]
	v_pk_add_f32 v[60:61], v[60:61], v[62:63]
	v_pk_add_f32 v[62:63], v[100:101], v[102:103]
	v_pk_add_f32 v[2:3], v[108:109], v[110:111]
	v_pk_add_f32 v[6:7], v[140:141], v[142:143]
	v_pk_add_f32 v[8:9], v[144:145], v[146:147]
	v_pk_add_f32 v[10:11], v[156:157], v[158:159]
	v_pk_add_f32 v[140:141], v[12:13], v[14:15]
	v_pk_add_f32 v[142:143], v[16:17], v[54:55]
	v_pk_add_f32 v[144:145], v[64:65], v[66:67]
	v_pk_add_f32 v[146:147], v[104:105], v[106:107]
	v_pk_add_f32 v[14:15], v[112:113], v[114:115]
	v_pk_add_f32 v[16:17], v[148:149], v[150:151]
	v_pk_add_f32 v[12:13], v[152:153], v[154:155]
	v_cmp_ne_u32_e64 s[74:75], 1, v4
	s_andn2_b64 vcc, exec, s[4:5]
	v_pk_add_f32 v[148:149], v[174:175], v[176:177]
	s_cbranch_vccnz .LBB0_289
; __device__ __forceinline__ int crow(int r, int hi) { return (r & 3) + 8 * (r >> 2) + 4 * hi; }
; template <bool NEED_SUM>
; __device__ __forceinline__ void sb_part1(SbTile& t, float& tsum, lds_cptr kslot, const bf16x8 (&qr)[4], bool masked, int qlim, int r32, int hi) {
;     ...
;     if (masked) {
;         asm volatile("; masked tile" ::: "memory");
; #pragma unroll
;         for (int r = 0; r < 16; ++r) { const int kv = crow(r, hi); if (kv >= qlim) l0[r] = 0.f; if (kv + 32 >= qlim) l1[r] = 0.f; }
;     }
	s_or_b64 vcc, s[68:69], s[64:65]
	v_cndmask_b32_e32 v10, 0, v10, vcc
	s_or_b64 vcc, vcc, s[60:61]
	v_cndmask_b32_e32 v9, 0, v9, vcc
	s_or_b64 vcc, vcc, s[56:57]
	v_cndmask_b32_e32 v8, 0, v8, vcc
	s_or_b64 vcc, vcc, s[52:53]
	v_cndmask_b32_e32 v7, 0, v7, vcc
	s_or_b64 vcc, vcc, s[48:49]
	v_cndmask_b32_e32 v6, 0, v6, vcc
	s_or_b64 vcc, vcc, s[44:45]
	v_cndmask_b32_e32 v3, 0, v3, vcc
	s_or_b64 vcc, vcc, s[40:41]
	v_cndmask_b32_e32 v2, 0, v2, vcc
	s_or_b64 vcc, vcc, s[36:37]
	v_cndmask_b32_e32 v63, 0, v63, vcc
	s_or_b64 vcc, vcc, s[30:31]
	v_cndmask_b32_e32 v62, 0, v62, vcc
	s_or_b64 vcc, vcc, s[26:27]
	v_cndmask_b32_e32 v61, 0, v61, vcc
	s_or_b64 vcc, vcc, s[22:23]
	v_cndmask_b32_e32 v60, 0, v60, vcc
	s_or_b64 vcc, vcc, s[18:19]
	v_cndmask_b32_e32 v59, 0, v59, vcc
	s_or_b64 vcc, vcc, s[14:15]
	v_cndmask_b32_e32 v58, 0, v58, vcc
	s_or_b64 vcc, vcc, s[10:11]
	v_cndmask_b32_e32 v57, 0, v57, vcc
	s_or_b64 vcc, vcc, s[6:7]
	v_cndmask_b32_e32 v56, 0, v56, vcc
	s_or_b64 vcc, s[70:71], s[66:67]
	v_cndmask_b32_e32 v148, 0, v148, vcc
	s_or_b64 vcc, vcc, s[62:63]
	v_cndmask_b32_e32 v13, 0, v13, vcc
	s_or_b64 vcc, vcc, s[58:59]
	v_cndmask_b32_e32 v12, 0, v12, vcc
	s_or_b64 vcc, vcc, s[54:55]
	v_cndmask_b32_e32 v17, 0, v17, vcc
	s_or_b64 vcc, vcc, s[50:51]
	v_cndmask_b32_e32 v16, 0, v16, vcc
	s_or_b64 vcc, vcc, s[46:47]
	v_cndmask_b32_e32 v15, 0, v15, vcc
	s_or_b64 vcc, vcc, s[42:43]
	v_cndmask_b32_e32 v14, 0, v14, vcc
	s_or_b64 vcc, vcc, s[38:39]
	v_cndmask_b32_e32 v147, 0, v147, vcc
	s_or_b64 vcc, vcc, s[34:35]
	v_cndmask_b32_e32 v146, 0, v146, vcc
	s_or_b64 vcc, vcc, s[28:29]
	v_cndmask_b32_e32 v145, 0, v145, vcc
	s_or_b64 vcc, vcc, s[24:25]
	v_cndmask_b32_e32 v144, 0, v144, vcc
	s_or_b64 vcc, vcc, s[20:21]
	v_cndmask_b32_e32 v143, 0, v143, vcc
	s_or_b64 vcc, vcc, s[16:17]
	v_cndmask_b32_e32 v142, 0, v142, vcc
	s_or_b64 vcc, vcc, s[12:13]
	v_cndmask_b32_e32 v141, 0, v141, vcc
	s_or_b64 vcc, vcc, s[8:9]
	v_cndmask_b32_e64 v11, 0, v11, s[68:69]
	v_cndmask_b32_e64 v149, 0, v149, s[70:71]
	v_cndmask_b32_e32 v140, 0, v140, vcc

; #define LAS __attribute__((address_space(3)))
; __device__ __forceinline__ int crow(int r, int hi) { return (r & 3) + 8 * (r >> 2) + 4 * hi; }
;     bf16x8 kf[8]; kfrags(kf, kslot, r32, hi);
;     f32x16 p0, p1;
; #pragma unroll
;     for (int g = 0; g < 4; ++g) { const f32x4 c0 = ld4(ckt + 8 * g), c1 = ld4(ckt + 32 + 8 * g);
; #pragma unroll
;         for (int i = 0; i < 4; ++i) { p0[4 * g + i] = c0[i]; p1[4 * g + i] = c1[i]; } }
;     u32x4 kn = {0u, 0xBF800000u, 0xBF80BF80u, 0u}; if (hi) { kn.y = 0u; kn.z = 0u; }
;     const bf16x8 kneg = __builtin_bit_cast(bf16x8, kn);
;     p0 = __builtin_amdgcn_mfma_f32_32x32x16_bf16(kneg, st.mq, p0, 0, 0, 0);
;     p1 = __builtin_amdgcn_mfma_f32_32x32x16_bf16(kneg, st.mq, p1, 0, 0, 0);
; #pragma unroll
;     for (int d0 = 0; d0 < 4; ++d0) {
;         p0 = __builtin_amdgcn_mfma_f32_32x32x16_bf16(kf[2 * d0], qr[d0], p0, 0, 0, 0);
;         p1 = __builtin_amdgcn_mfma_f32_32x32x16_bf16(kf[2 * d0 + 1], qr[d0], p1, 0, 0, 0);
;     }
;     __builtin_amdgcn_sched_barrier(0);
;     if (LEVEL == 2) { asm volatile("" :: "v"(p0), "v"(p1)); return; }
;     if (masked) {
;         asm volatile("; masked tile" ::: "memory");
; #pragma unroll
;         for (int r = 0; r < 16; ++r) { const int kv = crow(r, hi); if (kv >= qlim) p0[r] = NEG; if (kv + 32 >= qlim) p1[r] = NEG; }
;     }
; __device__ __forceinline__ void prompt_unit_fox(const Args& a, int l, int b, int h, int qb, LAS unsigned char* lds) {
;     ...
;         const lds_cptr kslot = (lds_cptr)lds + F_K + slot * 16384; const lds_cptr vp = vp0 + slot * 16384;
;         const LAS float* ck0 = (const LAS float*)(lds + F_CK) + (2 * jp) * 64 + 4 * hi;
;         if (pending) { fox_pair_pv(st, pp, vp0 + pslot * 16384); pending = false; }
;         if (jp < jpd) {
;             bool careful = false;
; #pragma unroll 1
;             for (int pass = 0; pass < 2; ++pass) { if (fox_pair_qs(st, pp, kslot, qr, (const LAS u32x2*)(lds + F_AUG) + (2 * jp) * 64 + r32, careful, r32, hi, wsf)) break; careful = true; }
;             if (lateB) { pending = true; pslot = slot; } else fox_pair_pv(st, pp, vp);
;         } else if (jp == jpd) {
;             if (jd & 1) { fox_tile(st, kslot + 8192, vp + 8192, qr, ck0 + 64, true, true, qlim, r32, hi, wsf); fox_tile(st, kslot, vp, qr, ck0, false, false, qlim, r32, hi, wsf); }
.LBB0_317:
	s_nop 9
	s_add_i32 s80, s3, 0
	s_lshl_b32 s81, s90, 7
	v_add_u32_e32 v190, s3, v180
	s_cmp_ge_i32 s90, s89
	s_mov_b64 s[4:5], -1
	s_cbranch_scc0 .LBB0_328
	v_mov_b64_e32 v[66:67], v[50:51]
	v_mov_b64_e32 v[82:83], v[34:35]
	v_mov_b64_e32 v[162:163], v[158:159]
	s_cmp_lg_u32 s90, s89
	v_mov_b64_e32 v[64:65], v[48:49]
	v_mov_b64_e32 v[62:63], v[46:47]
	v_mov_b64_e32 v[60:61], v[44:45]
	v_mov_b64_e32 v[58:59], v[42:43]
	v_mov_b64_e32 v[56:57], v[40:41]
	v_mov_b64_e32 v[54:55], v[38:39]
	v_mov_b64_e32 v[52:53], v[36:37]
	v_mov_b64_e32 v[80:81], v[32:33]
	v_mov_b64_e32 v[78:79], v[30:31]
	v_mov_b64_e32 v[76:77], v[28:29]
	v_mov_b64_e32 v[74:75], v[26:27]
	v_mov_b64_e32 v[72:73], v[24:25]
	v_mov_b64_e32 v[70:71], v[22:23]
	v_mov_b64_e32 v[68:69], v[20:21]
	v_mov_b64_e32 v[160:161], v[156:157]
	v_mov_b32_e32 v194, v192
	v_mov_b32_e32 v191, v193
	s_cbranch_scc1 .LBB0_327
	v_lshl_add_u32 v196, s81, 2, v184
	s_andn2_b64 vcc, exec, s[94:95]
	v_add3_u32 v195, s80, v173, v188
	s_cbranch_vccnz .LBB0_325
	ds_read_b128 v[68:71], v196 offset:256
	ds_read_b128 v[72:75], v196 offset:288
	ds_read_b128 v[76:79], v196 offset:320
	ds_read_b128 v[80:83], v196 offset:352
	ds_read_b128 v[52:55], v196 offset:384
	ds_read_b128 v[56:59], v196 offset:416
	ds_read_b128 v[60:63], v196 offset:448
	ds_read_b128 v[64:67], v196 offset:480
	ds_read_b128 v[84:87], v195 offset:8192
	s_waitcnt lgkmcnt(5)
	v_mfma_f32_32x32x16_bf16 v[68:83], v[120:123], v[156:159], v[68:83]
	s_waitcnt lgkmcnt(0)
	v_mfma_f32_32x32x16_bf16 v[68:83], v[84:87], v[6:9], v[68:83]
	ds_read_b128 v[84:87], v195 offset:8704
	v_mfma_f32_32x32x16_bf16 v[52:67], v[120:123], v[156:159], v[52:67]
	s_waitcnt lgkmcnt(0)
	v_mfma_f32_32x32x16_bf16 v[52:67], v[84:87], v[6:9], v[52:67]
	ds_read_b128 v[84:87], v195 offset:10240
	s_waitcnt lgkmcnt(0)
	v_mfma_f32_32x32x16_bf16 v[68:83], v[84:87], v[10:13], v[68:83]
	ds_read_b128 v[84:87], v195 offset:10752
	s_waitcnt lgkmcnt(0)
	v_mfma_f32_32x32x16_bf16 v[52:67], v[84:87], v[10:13], v[52:67]
	ds_read_b128 v[84:87], v195 offset:12288
	s_waitcnt lgkmcnt(0)
	v_mfma_f32_32x32x16_bf16 v[68:83], v[84:87], v[14:17], v[68:83]
	ds_read_b128 v[84:87], v195 offset:12800
	s_waitcnt lgkmcnt(0)
	v_mfma_f32_32x32x16_bf16 v[52:67], v[84:87], v[14:17], v[52:67]
	ds_read_b128 v[84:87], v195 offset:14336
	s_waitcnt lgkmcnt(0)
	v_mfma_f32_32x32x16_bf16 v[68:83], v[84:87], v[116:119], v[68:83]
	ds_read_b128 v[84:87], v195 offset:14848
	s_waitcnt lgkmcnt(0)
	v_mfma_f32_32x32x16_bf16 v[52:67], v[84:87], v[116:119], v[52:67]
	s_and_b64 vcc, s[70:71], s[66:67]
	s_nop 7
	v_cndmask_b32_e32 v82, v82, v18, vcc
	s_and_b64 vcc, vcc, s[62:63]
	v_cndmask_b32_e32 v81, v81, v18, vcc
	s_and_b64 vcc, vcc, s[58:59]
	v_cndmask_b32_e32 v80, v80, v18, vcc
	s_and_b64 vcc, vcc, s[54:55]
	v_cndmask_b32_e32 v79, v79, v18, vcc
	s_and_b64 vcc, vcc, s[50:51]
	v_cndmask_b32_e32 v78, v78, v18, vcc
	s_and_b64 vcc, vcc, s[46:47]
	v_cndmask_b32_e32 v77, v77, v18, vcc
	s_and_b64 vcc, vcc, s[42:43]
	v_cndmask_b32_e32 v76, v76, v18, vcc
	s_and_b64 vcc, vcc, s[38:39]
	v_cndmask_b32_e32 v75, v75, v18, vcc
	s_and_b64 vcc, vcc, s[34:35]
	v_cndmask_b32_e32 v74, v74, v18, vcc
	s_and_b64 vcc, vcc, s[28:29]
	v_cndmask_b32_e32 v73, v73, v18, vcc
	s_and_b64 vcc, vcc, s[24:25]
	v_cndmask_b32_e64 v3, v68, v18, s[8:9]
	v_cndmask_b32_e32 v72, v72, v18, vcc
	s_and_b64 vcc, vcc, s[20:21]
	v_cndmask_b32_e64 v3, v3, v68, s[12:13]
	v_cndmask_b32_e64 v4, v18, v69, s[12:13]
	v_cndmask_b32_e32 v71, v71, v18, vcc
	s_and_b64 vcc, vcc, s[16:17]
	v_cndmask_b32_e32 v69, v69, v4, vcc
	v_cndmask_b32_e32 v68, v68, v3, vcc
	v_cndmask_b32_e32 v70, v70, v18, vcc
	s_and_b64 vcc, s[72:73], s[68:69]
	v_cndmask_b32_e32 v66, v66, v18, vcc
	s_and_b64 vcc, vcc, s[64:65]
	v_cndmask_b32_e32 v65, v65, v18, vcc
	s_and_b64 vcc, vcc, s[60:61]
	v_cndmask_b32_e32 v64, v64, v18, vcc
	s_and_b64 vcc, vcc, s[56:57]
	v_cndmask_b32_e32 v63, v63, v18, vcc
	s_and_b64 vcc, vcc, s[52:53]
	v_cndmask_b32_e32 v62, v62, v18, vcc
	s_and_b64 vcc, vcc, s[48:49]
	v_cndmask_b32_e32 v61, v61, v18, vcc
	s_and_b64 vcc, vcc, s[44:45]
	v_cndmask_b32_e32 v60, v60, v18, vcc
	s_and_b64 vcc, vcc, s[40:41]
	v_cndmask_b32_e32 v59, v59, v18, vcc
	s_and_b64 vcc, vcc, s[36:37]
	v_cndmask_b32_e32 v58, v58, v18, vcc
	s_and_b64 vcc, vcc, s[30:31]
	v_cndmask_b32_e32 v57, v57, v18, vcc
	s_and_b64 vcc, vcc, s[26:27]
	v_cndmask_b32_e32 v56, v56, v18, vcc
	s_and_b64 vcc, vcc, s[22:23]
	v_cndmask_b32_e32 v55, v55, v18, vcc
	s_and_b64 vcc, vcc, s[18:19]
	v_cndmask_b32_e32 v54, v54, v18, vcc
	s_and_b64 vcc, vcc, s[14:15]
	v_cndmask_b32_e32 v53, v53, v18, vcc
	s_and_b64 vcc, vcc, s[10:11]
	v_cndmask_b32_e32 v52, v52, v18, vcc
	v_max_f32_e32 v3, v68, v68
	v_max_f32_e32 v4, v52, v52
	v_max_f32_e32 v3, v3, v4
	v_max3_f32 v4, v53, v70, v54
	v_max3_f32 v3, v3, v69, v71
	v_max3_f32 v4, v4, v72, v56
	v_max3_f32 v3, v3, v55, v73
	v_max3_f32 v4, v4, v74, v58
	v_max3_f32 v3, v3, v57, v75
	v_max3_f32 v4, v4, v76, v60
	v_max3_f32 v3, v3, v59, v77
	v_max3_f32 v4, v4, v78, v62
	v_max3_f32 v3, v3, v61, v79
	v_cndmask_b32_e64 v83, v83, v18, s[70:71]
	v_max3_f32 v4, v4, v80, v64
	v_max3_f32 v3, v3, v63, v81
	v_cndmask_b32_e64 v67, v67, v18, s[72:73]
	v_max3_f32 v4, v4, v82, v66
	v_max3_f32 v3, v3, v65, v83
	v_max3_f32 v3, v3, v67, v4
	v_mov_b32_e32 v4, v3
	s_nop 1
	v_permlane32_swap_b32_e32 v3, v4
	v_max_f32_e32 v4, v4, v4
	v_max_f32_e32 v3, v3, v3
	v_max_f32_e32 v84, v3, v4
	v_add_f32_e32 v191, v193, v84
	v_cvt_pk_bf16_f32 v3, v191, 0
	v_lshlrev_b32_e32 v3, 16, v3
	v_sub_f32_e32 v4, v191, v3
	v_cvt_pk_bf16_f32 v85, v4, 0
	v_lshlrev_b32_e32 v85, 16, v85
	v_sub_f32_e32 v4, v4, v85
	v_cvt_pk_bf16_f32 v3, 1.0, v3
; __device__ __forceinline__ unsigned cvtpk(float lo, float hi) { f32x2 v = {lo, hi}; bf16x2_t b = __builtin_convertvector(v, bf16x2_t); return __builtin_bit_cast(unsigned, b); }
; __device__ __forceinline__ float fadd_s(float a, float b) { float r = a + b; asm volatile("" : "+v"(r)); return r; }
; #define ATT_PACK4(P, B, F) (u32x4){F(P[B], P[B + 1]), F(P[B + 2], P[B + 3]), F(P[B + 4], P[B + 5]), F(P[B + 6], P[B + 7])}
;     bf16x8 kf[8]; kfrags(kf, kslot, r32, hi);
;     f32x16 p0, p1;
; #pragma unroll
;     for (int g = 0; g < 4; ++g) { const f32x4 c0 = ld4(ckt + 8 * g), c1 = ld4(ckt + 32 + 8 * g);
; #pragma unroll
;         for (int i = 0; i < 4; ++i) { p0[4 * g + i] = c0[i]; p1[4 * g + i] = c1[i]; } }
;     u32x4 kn = {0u, 0xBF800000u, 0xBF80BF80u, 0u}; if (hi) { kn.y = 0u; kn.z = 0u; }
;     const bf16x8 kneg = __builtin_bit_cast(bf16x8, kn);
;     p0 = __builtin_amdgcn_mfma_f32_32x32x16_bf16(kneg, st.mq, p0, 0, 0, 0);
;     p1 = __builtin_amdgcn_mfma_f32_32x32x16_bf16(kneg, st.mq, p1, 0, 0, 0);
; #pragma unroll
;     for (int d0 = 0; d0 < 4; ++d0) {
;         p0 = __builtin_amdgcn_mfma_f32_32x32x16_bf16(kf[2 * d0], qr[d0], p0, 0, 0, 0);
;         p1 = __builtin_amdgcn_mfma_f32_32x32x16_bf16(kf[2 * d0 + 1], qr[d0], p1, 0, 0, 0);
;     }
;     ...
;     VFrags vf; vfrags(vf, vp);
;     float sacc = 0.f, sacc2 = 0.f;
; #pragma unroll
;     for (int r = 0; r < 16; ++r) { p0[r] = __builtin_amdgcn_exp2f(p0[r]); p1[r] = __builtin_amdgcn_exp2f(p1[r]); sacc = fadd_s(sacc, p0[r]); sacc2 = fadd_s(sacc2, p1[r]); }
;     st.l = fadd_s(st.l, fadd_s(sacc, sacc2));
;     const u32x4 pw0 = ATT_PACK4(p0, 0, cvtpk), pw1 = ATT_PACK4(p0, 8, cvtpk), pw2 = ATT_PACK4(p1, 0, cvtpk), pw3 = ATT_PACK4(p1, 8, cvtpk);
;     __builtin_amdgcn_sched_barrier(0);
;     ...
;     pv(st.o, vf, pw0, pw1, pw2, pw3);
	v_cvt_pk_bf16_f32 v4, v85, v4
	v_cndmask_b32_e64 v4, 0, v4, s[6:7]
	v_cndmask_b32_e64 v3, 0, v3, s[6:7]
	v_sub_f32_e32 v68, v68, v84
	v_sub_f32_e32 v112, v52, v84
	v_sub_f32_e32 v69, v69, v84
	v_sub_f32_e32 v113, v53, v84
	v_sub_f32_e32 v70, v70, v84
	v_sub_f32_e32 v114, v54, v84
	v_sub_f32_e32 v71, v71, v84
	v_sub_f32_e32 v115, v55, v84
	v_sub_f32_e32 v72, v72, v84
	v_sub_f32_e32 v56, v56, v84
	v_sub_f32_e32 v73, v73, v84
	v_sub_f32_e32 v57, v57, v84
	v_sub_f32_e32 v74, v74, v84
	v_sub_f32_e32 v58, v58, v84
	v_sub_f32_e32 v75, v75, v84
	v_sub_f32_e32 v59, v59, v84
	v_sub_f32_e32 v76, v76, v84
	v_sub_f32_e32 v60, v60, v84
	v_sub_f32_e32 v77, v77, v84
	v_sub_f32_e32 v61, v61, v84
	v_sub_f32_e32 v78, v78, v84
	v_sub_f32_e32 v62, v62, v84
	v_sub_f32_e32 v79, v79, v84
	v_sub_f32_e32 v63, v63, v84
	v_sub_f32_e32 v80, v80, v84
	v_sub_f32_e32 v64, v64, v84
	v_sub_f32_e32 v81, v81, v84
	v_sub_f32_e32 v65, v65, v84
	v_sub_f32_e32 v82, v82, v84
	v_sub_f32_e32 v66, v66, v84
	v_sub_f32_e32 v83, v83, v84
	v_sub_f32_e32 v67, v67, v84
	v_exp_f32_e32 v68, v68
	v_exp_f32_e32 v164, v112
	v_exp_f32_e32 v69, v69
	v_exp_f32_e32 v165, v113
	v_add_f32_e32 v112, 0, v68
	v_exp_f32_e32 v70, v70
	ds_read_b64_tr_b16 v[52:53], v190 offset:57344
	ds_read_b64_tr_b16 v[54:55], v190 offset:57856
	ds_read_b64_tr_b16 v[84:85], v190 offset:58368
	ds_read_b64_tr_b16 v[86:87], v190 offset:58880
	ds_read_b64_tr_b16 v[88:89], v190 offset:59392
	ds_read_b64_tr_b16 v[90:91], v190 offset:59904
	ds_read_b64_tr_b16 v[92:93], v190 offset:60416
	ds_read_b64_tr_b16 v[94:95], v190 offset:60928
	ds_read_b64_tr_b16 v[96:97], v190 offset:61440
	ds_read_b64_tr_b16 v[98:99], v190 offset:61952
	ds_read_b64_tr_b16 v[100:101], v190 offset:62464
	ds_read_b64_tr_b16 v[102:103], v190 offset:62976
	ds_read_b64_tr_b16 v[104:105], v190 offset:63488
	ds_read_b64_tr_b16 v[106:107], v190 offset:64000
	ds_read_b64_tr_b16 v[108:109], v190 offset:64512
	ds_read_b64_tr_b16 v[110:111], v190 offset:65024
	v_exp_f32_e32 v166, v114
	v_add_f32_e32 v160, 0, v164
	v_add_f32_e32 v112, v112, v69
	v_exp_f32_e32 v71, v71
	v_exp_f32_e32 v167, v115
	v_add_f32_e32 v113, v160, v165
	v_add_f32_e32 v112, v112, v70
	v_exp_f32_e32 v72, v72
	v_add_f32_e32 v113, v113, v166
	v_exp_f32_e32 v56, v56
	v_add_f32_e32 v112, v112, v71
	v_exp_f32_e32 v73, v73
	v_add_f32_e32 v113, v113, v167
	v_exp_f32_e32 v57, v57
	v_add_f32_e32 v112, v112, v72
	v_exp_f32_e32 v74, v74
	v_add_f32_e32 v113, v113, v56
	v_exp_f32_e32 v58, v58
	v_add_f32_e32 v112, v112, v73
	v_exp_f32_e32 v75, v75
	v_add_f32_e32 v113, v113, v57
	v_exp_f32_e32 v59, v59
	v_add_f32_e32 v112, v112, v74
	v_exp_f32_e32 v76, v76
	v_add_f32_e32 v113, v113, v58
	v_exp_f32_e32 v60, v60
	v_add_f32_e32 v112, v112, v75
	v_exp_f32_e32 v77, v77
	v_add_f32_e32 v113, v113, v59
	v_exp_f32_e32 v61, v61
	v_add_f32_e32 v112, v76, v112
	v_exp_f32_e32 v78, v78
	v_add_f32_e32 v113, v60, v113
	v_exp_f32_e32 v62, v62
	v_add_f32_e32 v112, v77, v112
	v_exp_f32_e32 v79, v79
	v_add_f32_e32 v113, v61, v113
	v_exp_f32_e32 v63, v63
	v_add_f32_e32 v112, v78, v112
	v_exp_f32_e32 v80, v80
	v_add_f32_e32 v113, v62, v113
	v_exp_f32_e32 v64, v64
	v_add_f32_e32 v112, v79, v112
	v_exp_f32_e32 v81, v81
	v_add_f32_e32 v113, v63, v113
	v_exp_f32_e32 v65, v65
	v_add_f32_e32 v112, v80, v112
	v_exp_f32_e32 v82, v82
	v_add_f32_e32 v113, v64, v113
	v_exp_f32_e32 v66, v66
	v_add_f32_e32 v112, v81, v112
	v_exp_f32_e32 v83, v83
	v_add_f32_e32 v113, v65, v113
	v_exp_f32_e32 v67, v67
	v_add_f32_e32 v112, v82, v112
	v_add_f32_e32 v113, v66, v113
	v_add_f32_e32 v112, v83, v112
	v_add_f32_e32 v113, v67, v113
	v_cvt_pk_bf16_f32 v114, v72, v73
	v_add_f32_e32 v112, v112, v113
	v_cvt_pk_bf16_f32 v113, v70, v71
	v_add_f32_e32 v194, v192, v112
	v_cvt_pk_bf16_f32 v112, v68, v69
	v_cvt_pk_bf16_f32 v115, v74, v75
	v_cvt_pk_bf16_f32 v160, v76, v77
	v_cvt_pk_bf16_f32 v161, v78, v79
	v_cvt_pk_bf16_f32 v162, v80, v81
	v_cvt_pk_bf16_f32 v163, v82, v83
	v_cvt_pk_bf16_f32 v164, v164, v165
	v_cvt_pk_bf16_f32 v165, v166, v167
	v_cvt_pk_bf16_f32 v166, v56, v57
	v_cvt_pk_bf16_f32 v167, v58, v59
	v_cvt_pk_bf16_f32 v198, v60, v61
	v_cvt_pk_bf16_f32 v199, v62, v63
	v_cvt_pk_bf16_f32 v200, v64, v65
	v_cvt_pk_bf16_f32 v201, v66, v67
	s_waitcnt lgkmcnt(14)
	v_mfma_f32_32x32x16_bf16 v[68:83], v[112:115], v[52:55], v[20:35]
	s_waitcnt lgkmcnt(6)
	v_mfma_f32_32x32x16_bf16 v[52:67], v[112:115], v[96:99], v[36:51]
	v_mfma_f32_32x32x16_bf16 v[68:83], v[160:163], v[84:87], v[68:83]
	s_waitcnt lgkmcnt(4)
	v_mfma_f32_32x32x16_bf16 v[52:67], v[160:163], v[100:103], v[52:67]
	v_mfma_f32_32x32x16_bf16 v[68:83], v[164:167], v[88:91], v[68:83]
	s_waitcnt lgkmcnt(2)
	v_mfma_f32_32x32x16_bf16 v[52:67], v[164:167], v[104:107], v[52:67]
	v_mfma_f32_32x32x16_bf16 v[68:83], v[198:201], v[92:95], v[68:83]
	ds_read_b128 v[84:87], v196
	ds_read_b128 v[88:91], v196 offset:32
	ds_read_b128 v[92:95], v196 offset:64
	ds_read_b128 v[96:99], v196 offset:96
	s_waitcnt lgkmcnt(4)
	v_mfma_f32_32x32x16_bf16 v[52:67], v[198:201], v[108:111], v[52:67]
	ds_read_b128 v[100:103], v196 offset:128
	ds_read_b128 v[104:107], v196 offset:160
	ds_read_b128 v[108:111], v196 offset:192
	ds_read_b128 v[112:115], v196 offset:224
	ds_read_b128 v[160:163], v195
	ds_read_b128 v[164:167], v195 offset:512
	s_waitcnt lgkmcnt(6)
; #define LAS __attribute__((address_space(3)))
; __device__ __forceinline__ int crow(int r, int hi) { return (r & 3) + 8 * (r >> 2) + 4 * hi; }
; __device__ __forceinline__ float swap_max(float m) { auto rr = __builtin_amdgcn_permlane32_swap(__float_as_uint(m), __float_as_uint(m), false, false); return fmaxf(__uint_as_float(rr[0]), __uint_as_float(rr[1])); }
; __device__ __forceinline__ float max3f(float a, float b, float c) { return __builtin_fmaxf(__builtin_fmaxf(a, b), c); }
; #define ATT_LDS_WAIT() asm volatile("s_waitcnt lgkmcnt(0)" ::: "memory")
;     ...
;     for (int d0 = 0; d0 < 4; ++d0) {
;         p0 = __builtin_amdgcn_mfma_f32_32x32x16_bf16(kf[2 * d0], qr[d0], p0, 0, 0, 0);
;         p1 = __builtin_amdgcn_mfma_f32_32x32x16_bf16(kf[2 * d0 + 1], qr[d0], p1, 0, 0, 0);
;     }
;     __builtin_amdgcn_sched_barrier(0);
;     if (LEVEL == 2) { asm volatile("" :: "v"(p0), "v"(p1)); return; }
;     if (masked) {
;         asm volatile("; masked tile" ::: "memory");
; #pragma unroll
;         for (int r = 0; r < 16; ++r) { const int kv = crow(r, hi); if (kv >= qlim) p0[r] = NEG; if (kv + 32 >= qlim) p1[r] = NEG; }
;     }
;     float rm = max3f(p0[0], p1[0], p0[1]), rm2 = max3f(p1[1], p0[2], p1[2]);
; #pragma unroll
;     for (int r = 3; r < 15; r += 2) { rm = max3f(rm, p0[r], p1[r]); rm2 = max3f(rm2, p0[r + 1], p1[r + 1]); }
;     rm = max3f(rm, p0[15], p1[15]); rm = swap_max(max3f(rm, rm2, rm2));
;     if (first || __any(rm > FOX_THR)) {
;         const float dl = first ? rm : fmaxf(rm, 0.f);
;         st.m += dl; st.mq = make_mq(st.m, hi);
; #pragma unroll
;         for (int r = 0; r < 16; ++r) { p0[r] -= dl; p1[r] -= dl; }
;         if (!first) {
;             const float f = __builtin_amdgcn_exp2f(-dl);
;             st.l *= f;
;             if (hi == 0) wsf[r32] = f;
;             ATT_LDS_WAIT();
; #pragma unroll
;             for (int g = 0; g < 4; ++g) { const f32x4 fv = *(const LAS f32x4*)(wsf + 8 * g + 4 * hi);
; #pragma unroll
;                 for (int i = 0; i < 4; ++i) { st.o[0][4 * g + i] *= fv[i]; st.o[1][4 * g + i] *= fv[i]; } }
;         }
;     }
	v_mfma_f32_32x32x16_bf16 v[84:99], v[120:123], v[2:5], v[84:99]
	s_waitcnt lgkmcnt(2)
	v_mfma_f32_32x32x16_bf16 v[100:115], v[120:123], v[2:5], v[100:115]
	s_waitcnt lgkmcnt(1)
	v_mfma_f32_32x32x16_bf16 v[84:99], v[160:163], v[6:9], v[84:99]
	s_waitcnt lgkmcnt(0)
	v_mfma_f32_32x32x16_bf16 v[100:115], v[164:167], v[6:9], v[100:115]
	ds_read_b128 v[160:163], v195 offset:2048
	ds_read_b128 v[164:167], v195 offset:2560
	s_waitcnt lgkmcnt(1)
	v_mfma_f32_32x32x16_bf16 v[84:99], v[160:163], v[10:13], v[84:99]
	s_waitcnt lgkmcnt(0)
	v_mfma_f32_32x32x16_bf16 v[100:115], v[164:167], v[10:13], v[100:115]
	ds_read_b128 v[160:163], v195 offset:4096
	ds_read_b128 v[164:167], v195 offset:4608
	s_waitcnt lgkmcnt(1)
	v_mfma_f32_32x32x16_bf16 v[84:99], v[160:163], v[14:17], v[84:99]
	s_waitcnt lgkmcnt(0)
	v_mfma_f32_32x32x16_bf16 v[100:115], v[164:167], v[14:17], v[100:115]
	ds_read_b128 v[160:163], v195 offset:6144
	ds_read_b128 v[164:167], v195 offset:6656
	s_waitcnt lgkmcnt(1)
	v_mfma_f32_32x32x16_bf16 v[84:99], v[160:163], v[116:119], v[84:99]
	s_waitcnt lgkmcnt(0)
	v_mfma_f32_32x32x16_bf16 v[100:115], v[164:167], v[116:119], v[100:115]
	s_nop 11
	v_max_f32_e32 v160, v100, v100
	v_max_f32_e32 v161, v84, v84
	v_max_f32_e32 v160, v161, v160
	v_max3_f32 v161, v101, v86, v102
	v_max3_f32 v160, v160, v85, v87
	v_max3_f32 v161, v161, v88, v104
	v_max3_f32 v160, v160, v103, v89
	v_max3_f32 v161, v161, v90, v106
	v_max3_f32 v160, v160, v105, v91
	v_max3_f32 v161, v161, v92, v108
	v_max3_f32 v160, v160, v107, v93
	v_max3_f32 v161, v161, v94, v110
	v_max3_f32 v160, v160, v109, v95
	v_max3_f32 v161, v161, v96, v112
	v_max3_f32 v160, v160, v111, v97
	v_max3_f32 v161, v161, v98, v114
	v_max3_f32 v160, v160, v113, v99
	v_max3_f32 v160, v160, v115, v161
	v_mov_b32_e32 v161, v160
	s_nop 1
	v_permlane32_swap_b32_e32 v160, v161
	v_max_f32_e32 v161, v161, v161
	v_max_f32_e32 v160, v160, v160
	v_max_f32_e32 v160, v160, v161
	s_mov_b32 s3, 0x41000000
	v_cmp_lt_f32_e32 vcc, s3, v160
	s_cbranch_vccz .LBB0_324
	v_max_f32_e32 v160, 0, v160
	v_exp_f32_e64 v161, -v160
	s_and_saveexec_b64 s[4:5], s[6:7]
	ds_write_b32 v182, v161
	s_or_b64 exec, exec, s[4:5]
	v_add_f32_e32 v191, v191, v160
	v_cvt_pk_bf16_f32 v3, v191, 0
	v_lshlrev_b32_e32 v3, 16, v3
	v_sub_f32_e32 v4, v191, v3
	v_cvt_pk_bf16_f32 v162, v4, 0
	v_lshlrev_b32_e32 v162, 16, v162
	v_sub_f32_e32 v4, v4, v162
	s_waitcnt lgkmcnt(0)
	v_add_u32_e32 v197, s78, v172
	v_cvt_pk_bf16_f32 v4, v162, v4
	v_pk_add_f32 v[84:85], v[84:85], v[160:161] op_sel_hi:[1,0] neg_lo:[0,1] neg_hi:[0,1]
	v_pk_add_f32 v[100:101], v[100:101], v[160:161] op_sel_hi:[1,0] neg_lo:[0,1] neg_hi:[0,1]
	v_pk_add_f32 v[86:87], v[86:87], v[160:161] op_sel_hi:[1,0] neg_lo:[0,1] neg_hi:[0,1]
	v_pk_add_f32 v[102:103], v[102:103], v[160:161] op_sel_hi:[1,0] neg_lo:[0,1] neg_hi:[0,1]
	v_pk_add_f32 v[88:89], v[88:89], v[160:161] op_sel_hi:[1,0] neg_lo:[0,1] neg_hi:[0,1]
	v_pk_add_f32 v[104:105], v[104:105], v[160:161] op_sel_hi:[1,0] neg_lo:[0,1] neg_hi:[0,1]
	v_pk_add_f32 v[90:91], v[90:91], v[160:161] op_sel_hi:[1,0] neg_lo:[0,1] neg_hi:[0,1]
	v_pk_add_f32 v[106:107], v[106:107], v[160:161] op_sel_hi:[1,0] neg_lo:[0,1] neg_hi:[0,1]
	v_pk_add_f32 v[92:93], v[92:93], v[160:161] op_sel_hi:[1,0] neg_lo:[0,1] neg_hi:[0,1]
	v_pk_add_f32 v[108:109], v[108:109], v[160:161] op_sel_hi:[1,0] neg_lo:[0,1] neg_hi:[0,1]
	v_pk_add_f32 v[94:95], v[94:95], v[160:161] op_sel_hi:[1,0] neg_lo:[0,1] neg_hi:[0,1]
	v_pk_add_f32 v[110:111], v[110:111], v[160:161] op_sel_hi:[1,0] neg_lo:[0,1] neg_hi:[0,1]
	v_pk_add_f32 v[96:97], v[96:97], v[160:161] op_sel_hi:[1,0] neg_lo:[0,1] neg_hi:[0,1]
	v_pk_add_f32 v[112:113], v[112:113], v[160:161] op_sel_hi:[1,0] neg_lo:[0,1] neg_hi:[0,1]
	v_pk_add_f32 v[98:99], v[98:99], v[160:161] op_sel_hi:[1,0] neg_lo:[0,1] neg_hi:[0,1]
	v_pk_add_f32 v[114:115], v[114:115], v[160:161] op_sel_hi:[1,0] neg_lo:[0,1] neg_hi:[0,1]
	v_mul_f32_e32 v194, v194, v161
	ds_read_b128 v[160:163], v197
	ds_read_b128 v[164:167], v197 offset:32
	ds_read_b128 v[198:201], v197 offset:64
	ds_read_b128 v[202:205], v197 offset:96
	v_cvt_pk_bf16_f32 v3, 1.0, v3
	v_cndmask_b32_e64 v4, 0, v4, s[6:7]
	v_cndmask_b32_e64 v3, 0, v3, s[6:7]
	s_waitcnt lgkmcnt(1)
	v_pk_mul_f32 v[76:77], v[76:77], v[198:199]
	s_waitcnt lgkmcnt(0)
	v_pk_mul_f32 v[80:81], v[80:81], v[202:203]
	v_pk_mul_f32 v[72:73], v[72:73], v[164:165]
	v_pk_mul_f32 v[82:83], v[82:83], v[204:205]
	v_pk_mul_f32 v[78:79], v[78:79], v[200:201]
	v_pk_mul_f32 v[74:75], v[74:75], v[166:167]
	v_pk_mul_f32 v[70:71], v[70:71], v[162:163]
	v_pk_mul_f32 v[68:69], v[68:69], v[160:161]
	v_pk_mul_f32 v[64:65], v[64:65], v[202:203]
	v_pk_mul_f32 v[60:61], v[60:61], v[198:199]
	v_pk_mul_f32 v[56:57], v[56:57], v[164:165]
	v_pk_mul_f32 v[66:67], v[66:67], v[204:205]
	v_pk_mul_f32 v[62:63], v[62:63], v[200:201]
	v_pk_mul_f32 v[58:59], v[58:59], v[166:167]
	v_pk_mul_f32 v[54:55], v[54:55], v[162:163]
	v_pk_mul_f32 v[52:53], v[52:53], v[160:161]

; template <bool NEED_SUM>
; __device__ __forceinline__ void sb_part1(SbTile& t, float& tsum, lds_cptr kslot, const bf16x8 (&qr)[4], bool masked, int qlim, int r32, int hi) {
;     bf16x8 kf[8]; kfrags(kf, kslot, r32, hi);
;     t.z0 = (f32x16){}; t.z1 = (f32x16){};
; #pragma unroll
;     for (int d0 = 0; d0 < 4; ++d0) {
;         t.z0 = __builtin_amdgcn_mfma_f32_32x32x16_bf16(kf[2 * d0], qr[d0], t.z0, 0, 0, 0);
;         t.z1 = __builtin_amdgcn_mfma_f32_32x32x16_bf16(kf[2 * d0 + 1], qr[d0], t.z1, 0, 0, 0);
;     }
;     __builtin_amdgcn_sched_barrier(0);
;     f32x16 l0, l1;
; #pragma unroll
;     for (int r = 0; r < 16; ++r) {
;         const float a0 = t.z0[r], a1 = t.z1[r];
;         l0[r] = fmaxf(a0, 0.f) + __builtin_amdgcn_logf(1.0f + __builtin_amdgcn_exp2f(-__builtin_fabsf(a0)));
;         l1[r] = fmaxf(a1, 0.f) + __builtin_amdgcn_logf(1.0f + __builtin_amdgcn_exp2f(-__builtin_fabsf(a1)));
;     }
.LBB0_416:
	s_or_b64 exec, exec, s[4:5]
	s_waitcnt vmcnt(0)
	v_cvt_pk_bf16_f32 v2, v10, v11
	v_cvt_pk_bf16_f32 v3, v12, v13
	v_cvt_pk_bf16_f32 v6, v6, v7
	v_cvt_pk_bf16_f32 v7, v8, v9
	v_add_u32_e32 v4, 0x2800, v236
	ds_write2_b64 v4, v[2:3], v[6:7] offset1:32
	v_cvt_pk_bf16_f32 v2, v52, v53
	v_cvt_pk_bf16_f32 v3, v54, v55
	v_cvt_pk_bf16_f32 v6, v14, v15
	v_cvt_pk_bf16_f32 v7, v16, v17
	ds_write2_b64 v4, v[2:3], v[6:7] offset0:64 offset1:96
	v_cvt_pk_bf16_f32 v2, v60, v61
	v_cvt_pk_bf16_f32 v3, v62, v63
	v_cvt_pk_bf16_f32 v6, v56, v57
	v_cvt_pk_bf16_f32 v7, v58, v59
	ds_write2_b64 v4, v[2:3], v[6:7] offset0:128 offset1:160
	v_cvt_pk_bf16_f32 v2, v68, v69
	v_cvt_pk_bf16_f32 v3, v70, v71
	v_cvt_pk_bf16_f32 v6, v64, v65
	v_cvt_pk_bf16_f32 v7, v66, v67
	ds_write2_b64 v4, v[2:3], v[6:7] offset0:192 offset1:224
	s_waitcnt lgkmcnt(0)
	ds_read_b128 v[6:9], v233
	s_waitcnt lgkmcnt(0)
	v_mfma_f32_32x32x16_bf16 v[52:67], v[6:9], v[124:127], 0
	ds_read_b128 v[6:9], v233 offset:512
	s_waitcnt lgkmcnt(0)
	v_mfma_f32_32x32x16_bf16 v[68:83], v[6:9], v[124:127], 0
	ds_read_b128 v[6:9], v233 offset:2048
	s_waitcnt lgkmcnt(0)
	v_mfma_f32_32x32x16_bf16 v[52:67], v[6:9], v[128:131], v[52:67]
	ds_read_b128 v[6:9], v233 offset:2560
	s_waitcnt lgkmcnt(0)
	v_mfma_f32_32x32x16_bf16 v[68:83], v[6:9], v[128:131], v[68:83]
	ds_read_b128 v[6:9], v233 offset:4096
	s_waitcnt lgkmcnt(0)
	v_mfma_f32_32x32x16_bf16 v[52:67], v[6:9], v[132:135], v[52:67]
	ds_read_b128 v[6:9], v233 offset:4608
	s_waitcnt lgkmcnt(0)
	v_mfma_f32_32x32x16_bf16 v[68:83], v[6:9], v[132:135], v[68:83]
	ds_read_b128 v[6:9], v233 offset:6144
	s_waitcnt lgkmcnt(0)
	v_mfma_f32_32x32x16_bf16 v[52:67], v[6:9], v[136:139], v[52:67]
	ds_read_b128 v[6:9], v233 offset:6656
	s_waitcnt lgkmcnt(0)
	v_mfma_f32_32x32x16_bf16 v[68:83], v[6:9], v[136:139], v[68:83]
	s_nop 8
	v_exp_f32_e64 v4, -|v53|
	v_exp_f32_e64 v9, -|v54|
	v_exp_f32_e64 v11, -|v55|
	v_exp_f32_e64 v13, -|v56|
	v_add_f32_e32 v4, 1.0, v4
	v_log_f32_e32 v7, v4
	v_max_f32_e32 v8, 0, v54
	v_add_f32_e32 v4, 1.0, v9
	v_log_f32_e32 v10, v4
	v_max_f32_e32 v9, 0, v55
	v_add_f32_e32 v4, 1.0, v11
	v_exp_f32_e64 v15, -|v57|
	v_log_f32_e32 v11, v4
	v_max_f32_e32 v12, 0, v56
	v_add_f32_e32 v4, 1.0, v13
	v_exp_f32_e64 v17, -|v58|
	v_log_f32_e32 v14, v4
	v_max_f32_e32 v13, 0, v57
	v_add_f32_e32 v4, 1.0, v15
	v_exp_f32_e64 v85, -|v59|
	v_log_f32_e32 v15, v4
	v_max_f32_e32 v16, 0, v58
	v_add_f32_e32 v4, 1.0, v17
	v_exp_f32_e64 v87, -|v60|
	v_log_f32_e32 v84, v4
	v_max_f32_e32 v17, 0, v59
	v_add_f32_e32 v4, 1.0, v85
	v_exp_f32_e64 v89, -|v61|
	v_log_f32_e32 v85, v4
	v_max_f32_e32 v86, 0, v60
	v_add_f32_e32 v4, 1.0, v87
	v_exp_f32_e64 v91, -|v62|
	v_log_f32_e32 v88, v4
	v_max_f32_e32 v87, 0, v61
	v_add_f32_e32 v4, 1.0, v89
	v_exp_f32_e64 v93, -|v63|
	v_log_f32_e32 v89, v4
	v_max_f32_e32 v90, 0, v62
	v_add_f32_e32 v4, 1.0, v91
	v_exp_f32_e64 v95, -|v64|
	v_log_f32_e32 v92, v4
	v_max_f32_e32 v91, 0, v63
	v_add_f32_e32 v4, 1.0, v93
	v_exp_f32_e64 v97, -|v65|
	v_log_f32_e32 v93, v4
	v_max_f32_e32 v94, 0, v64
	v_add_f32_e32 v4, 1.0, v95
	v_exp_f32_e64 v99, -|v66|
	v_log_f32_e32 v96, v4
	v_exp_f32_e64 v3, -|v52|
	v_max_f32_e32 v95, 0, v65
	v_add_f32_e32 v4, 1.0, v97
	v_exp_f32_e64 v101, -|v67|
	v_log_f32_e32 v97, v4
	v_max_f32_e32 v98, 0, v66
	v_add_f32_e32 v4, 1.0, v99
	v_log_f32_e32 v100, v4
	v_add_f32_e32 v3, 1.0, v3
	v_max_f32_e32 v99, 0, v67
	v_add_f32_e32 v4, 1.0, v101
	v_log_f32_e32 v6, v3
	v_log_f32_e32 v101, v4
	v_max_f32_e32 v2, 0, v52
	v_max_f32_e32 v3, 0, v53
	v_pk_add_f32 v[2:3], v[2:3], v[6:7]
	v_pk_add_f32 v[8:9], v[8:9], v[10:11]
	v_pk_add_f32 v[10:11], v[12:13], v[14:15]
	v_pk_add_f32 v[12:13], v[16:17], v[84:85]
	v_pk_add_f32 v[14:15], v[86:87], v[88:89]
	v_pk_add_f32 v[16:17], v[90:91], v[92:93]
	v_pk_add_f32 v[84:85], v[94:95], v[96:97]
	v_pk_add_f32 v[86:87], v[98:99], v[100:101]
	s_and_b64 vcc, exec, s[66:67]
	s_cbranch_vccnz .LBB0_419
	v_exp_f32_e64 v4, -|v68|
	v_exp_f32_e64 v89, -|v69|
	v_exp_f32_e64 v91, -|v70|
	v_exp_f32_e64 v93, -|v71|
	v_add_f32_e32 v4, 1.0, v4
	v_log_f32_e32 v88, v4
	v_max_f32_e32 v7, 0, v69
	v_add_f32_e32 v4, 1.0, v89
	v_log_f32_e32 v89, v4
	v_max_f32_e32 v90, 0, v70
	v_add_f32_e32 v4, 1.0, v91
	v_exp_f32_e64 v95, -|v72|
	v_log_f32_e32 v92, v4
	v_max_f32_e32 v91, 0, v71
	v_add_f32_e32 v4, 1.0, v93
	v_exp_f32_e64 v97, -|v73|
	v_log_f32_e32 v93, v4
	v_max_f32_e32 v94, 0, v72
	v_add_f32_e32 v4, 1.0, v95
	v_exp_f32_e64 v99, -|v74|
	v_log_f32_e32 v96, v4
	v_max_f32_e32 v95, 0, v73
	v_add_f32_e32 v4, 1.0, v97
	v_exp_f32_e64 v101, -|v75|
	v_log_f32_e32 v97, v4
	v_max_f32_e32 v98, 0, v74
	v_add_f32_e32 v4, 1.0, v99
	v_exp_f32_e64 v103, -|v76|
	v_log_f32_e32 v100, v4
	v_max_f32_e32 v99, 0, v75
	v_add_f32_e32 v4, 1.0, v101
	v_exp_f32_e64 v105, -|v77|
	v_log_f32_e32 v101, v4
	v_max_f32_e32 v102, 0, v76
	v_add_f32_e32 v4, 1.0, v103
	v_log_f32_e32 v106, v4
	v_max_f32_e32 v103, 0, v77
	v_add_f32_e32 v4, 1.0, v105
	v_exp_f32_e64 v105, -|v78|
	v_log_f32_e32 v107, v4
	v_max_f32_e32 v108, 0, v78
	v_add_f32_e32 v4, 1.0, v105
	v_exp_f32_e64 v105, -|v79|
	v_log_f32_e32 v110, v4
	v_max_f32_e32 v109, 0, v79
	v_add_f32_e32 v4, 1.0, v105
	v_exp_f32_e64 v105, -|v80|
	v_log_f32_e32 v111, v4
	v_max_f32_e32 v112, 0, v80
	v_add_f32_e32 v4, 1.0, v105
	v_exp_f32_e64 v105, -|v81|
	v_log_f32_e32 v114, v4
	v_max_f32_e32 v113, 0, v81
	v_add_f32_e32 v4, 1.0, v105
	v_exp_f32_e64 v105, -|v82|
	v_log_f32_e32 v115, v4
	v_max_f32_e32 v140, 0, v82
	v_add_f32_e32 v4, 1.0, v105
	v_exp_f32_e64 v105, -|v83|
	v_log_f32_e32 v142, v4
	v_max_f32_e32 v141, 0, v83
	v_add_f32_e32 v4, 1.0, v105
	v_log_f32_e32 v143, v4
	v_max_f32_e32 v6, 0, v68
	v_pk_add_f32 v[88:89], v[6:7], v[88:89]
	v_pk_add_f32 v[90:91], v[90:91], v[92:93]
	v_pk_add_f32 v[94:95], v[94:95], v[96:97]
	v_pk_add_f32 v[98:99], v[98:99], v[100:101]
	v_pk_add_f32 v[92:93], v[102:103], v[106:107]
	v_pk_add_f32 v[96:97], v[108:109], v[110:111]
	v_pk_add_f32 v[100:101], v[112:113], v[114:115]
	v_pk_add_f32 v[102:103], v[140:141], v[142:143]
	s_branch .LBB0_420

; template <bool NEED_SUM>
; __device__ __forceinline__ void sb_part1(SbTile& t, float& tsum, lds_cptr kslot, const bf16x8 (&qr)[4], bool masked, int qlim, int r32, int hi) {
;     bf16x8 kf[8]; kfrags(kf, kslot, r32, hi);
;     t.z0 = (f32x16){}; t.z1 = (f32x16){};
; #pragma unroll
;     for (int d0 = 0; d0 < 4; ++d0) {
;         t.z0 = __builtin_amdgcn_mfma_f32_32x32x16_bf16(kf[2 * d0], qr[d0], t.z0, 0, 0, 0);
;         t.z1 = __builtin_amdgcn_mfma_f32_32x32x16_bf16(kf[2 * d0 + 1], qr[d0], t.z1, 0, 0, 0);
;     }
;     __builtin_amdgcn_sched_barrier(0);
;     f32x16 l0, l1;
; #pragma unroll
;     for (int r = 0; r < 16; ++r) {
;         const float a0 = t.z0[r], a1 = t.z1[r];
;         l0[r] = fmaxf(a0, 0.f) + __builtin_amdgcn_logf(1.0f + __builtin_amdgcn_exp2f(-__builtin_fabsf(a0)));
;         l1[r] = fmaxf(a1, 0.f) + __builtin_amdgcn_logf(1.0f + __builtin_amdgcn_exp2f(-__builtin_fabsf(a1)));
;     }
.LBB0_947:
	s_add_i32 s80, s97, s33
	s_cmp_lt_i32 s80, 0
	s_cselect_b64 s[76:77], -1, 0
	s_or_b64 s[76:77], s[76:77], s[74:75]
	s_and_b64 vcc, exec, s[76:77]
	s_cbranch_vccnz .LBB0_953
	s_add_i32 s74, s95, s96
	s_add_i32 s74, s74, 0x8000
	s_and_b32 s81, s74, 0xe000
	v_add_u32_e32 v2, s81, v172
	ds_read_b128 v[6:9], v2
	s_waitcnt lgkmcnt(0)
	v_mfma_f32_32x32x16_bf16 v[68:83], v[6:9], v[124:127], 0
	ds_read_b128 v[6:9], v2 offset:512
	s_waitcnt lgkmcnt(0)
	v_mfma_f32_32x32x16_bf16 v[84:99], v[6:9], v[124:127], 0
	ds_read_b128 v[6:9], v2 offset:2048
	s_waitcnt lgkmcnt(0)
	v_mfma_f32_32x32x16_bf16 v[68:83], v[6:9], v[128:131], v[68:83]
	ds_read_b128 v[6:9], v2 offset:2560
	s_waitcnt lgkmcnt(0)
	v_mfma_f32_32x32x16_bf16 v[84:99], v[6:9], v[128:131], v[84:99]
	ds_read_b128 v[6:9], v2 offset:4096
	s_waitcnt lgkmcnt(0)
	v_mfma_f32_32x32x16_bf16 v[68:83], v[6:9], v[132:135], v[68:83]
	ds_read_b128 v[6:9], v2 offset:4608
	s_waitcnt lgkmcnt(0)
	v_mfma_f32_32x32x16_bf16 v[84:99], v[6:9], v[132:135], v[84:99]
	ds_read_b128 v[6:9], v2 offset:6144
	s_waitcnt lgkmcnt(0)
	v_mfma_f32_32x32x16_bf16 v[68:83], v[6:9], v[136:139], v[68:83]
	ds_read_b128 v[6:9], v2 offset:6656
	s_waitcnt lgkmcnt(0)
	v_mfma_f32_32x32x16_bf16 v[84:99], v[6:9], v[136:139], v[84:99]
	s_nop 8
	v_exp_f32_e64 v3, -|v68|
	s_nop 1
	v_exp_f32_e64 v4, -|v84|
	v_exp_f32_e64 v8, -|v85|
	v_exp_f32_e64 v9, -|v70|
	v_add_f32_e32 v3, 1.0, v3
	v_log_f32_e32 v6, v3
	v_max_f32_e32 v12, 0, v84
	v_add_f32_e32 v3, 1.0, v4
	v_exp_f32_e64 v4, -|v69|
	v_exp_f32_e64 v11, -|v71|
	v_exp_f32_e64 v53, -|v87|
	v_log_f32_e32 v14, v3
	v_add_f32_e32 v4, 1.0, v4
	v_log_f32_e32 v7, v4
	v_max_f32_e32 v13, 0, v85
	v_add_f32_e32 v4, 1.0, v8
	v_log_f32_e32 v15, v4
	v_max_f32_e32 v8, 0, v70
	v_add_f32_e32 v4, 1.0, v9
	v_exp_f32_e64 v9, -|v86|
	v_log_f32_e32 v10, v4
	v_max_f32_e32 v16, 0, v86
	v_add_f32_e32 v4, 1.0, v9
	v_log_f32_e32 v54, v4
	v_max_f32_e32 v9, 0, v71
	v_add_f32_e32 v4, 1.0, v11
	v_log_f32_e32 v11, v4
	v_max_f32_e32 v17, 0, v87
	v_add_f32_e32 v4, 1.0, v53
	v_exp_f32_e64 v53, -|v72|
	v_log_f32_e32 v55, v4
	v_max_f32_e32 v60, 0, v72
	v_add_f32_e32 v4, 1.0, v53
	v_exp_f32_e64 v53, -|v88|
	v_log_f32_e32 v62, v4
	v_max_f32_e32 v64, 0, v88
	v_add_f32_e32 v4, 1.0, v53
	v_exp_f32_e64 v53, -|v73|
	v_log_f32_e32 v66, v4
	v_max_f32_e32 v61, 0, v73
	v_add_f32_e32 v4, 1.0, v53
	v_exp_f32_e64 v53, -|v89|
	v_log_f32_e32 v63, v4
	v_max_f32_e32 v65, 0, v89
	v_add_f32_e32 v4, 1.0, v53
	v_exp_f32_e64 v53, -|v74|
	v_log_f32_e32 v67, v4
	v_max_f32_e32 v100, 0, v74
	v_add_f32_e32 v4, 1.0, v53
	v_exp_f32_e64 v53, -|v90|
	v_log_f32_e32 v102, v4
	v_max_f32_e32 v104, 0, v90
	v_add_f32_e32 v4, 1.0, v53
	v_exp_f32_e64 v53, -|v75|
	v_log_f32_e32 v106, v4
	v_max_f32_e32 v101, 0, v75
	v_add_f32_e32 v4, 1.0, v53
	v_exp_f32_e64 v53, -|v91|
	v_log_f32_e32 v103, v4
	v_max_f32_e32 v105, 0, v91
	v_add_f32_e32 v4, 1.0, v53
	v_exp_f32_e64 v53, -|v76|
	v_log_f32_e32 v107, v4
	v_max_f32_e32 v108, 0, v76
	v_add_f32_e32 v4, 1.0, v53
	v_exp_f32_e64 v53, -|v92|
	v_log_f32_e32 v110, v4
	v_max_f32_e32 v112, 0, v92
	v_add_f32_e32 v4, 1.0, v53
	v_exp_f32_e64 v53, -|v77|
	v_log_f32_e32 v114, v4
	v_max_f32_e32 v109, 0, v77
	v_add_f32_e32 v4, 1.0, v53
	v_exp_f32_e64 v53, -|v93|
	v_log_f32_e32 v111, v4
	v_max_f32_e32 v113, 0, v93
	v_add_f32_e32 v4, 1.0, v53
	v_exp_f32_e64 v53, -|v78|
	v_log_f32_e32 v115, v4
	v_max_f32_e32 v140, 0, v78
	v_add_f32_e32 v4, 1.0, v53
	v_exp_f32_e64 v53, -|v94|
	v_log_f32_e32 v142, v4
	v_max_f32_e32 v148, 0, v94
	v_add_f32_e32 v4, 1.0, v53
	v_exp_f32_e64 v53, -|v79|
	v_log_f32_e32 v150, v4
	v_max_f32_e32 v141, 0, v79
	v_add_f32_e32 v4, 1.0, v53
	v_exp_f32_e64 v53, -|v95|
	v_log_f32_e32 v143, v4
	v_max_f32_e32 v149, 0, v95
	v_add_f32_e32 v4, 1.0, v53
	v_exp_f32_e64 v53, -|v80|
	v_log_f32_e32 v151, v4
	v_max_f32_e32 v144, 0, v80
	v_add_f32_e32 v4, 1.0, v53
	v_exp_f32_e64 v53, -|v96|
	v_log_f32_e32 v146, v4
	v_max_f32_e32 v152, 0, v96
	v_add_f32_e32 v4, 1.0, v53
	v_exp_f32_e64 v53, -|v81|
	v_log_f32_e32 v154, v4
	v_max_f32_e32 v145, 0, v81
	v_add_f32_e32 v4, 1.0, v53
	v_exp_f32_e64 v53, -|v97|
	v_log_f32_e32 v147, v4
	v_max_f32_e32 v153, 0, v97
	v_add_f32_e32 v4, 1.0, v53
	v_exp_f32_e64 v53, -|v82|
	v_log_f32_e32 v155, v4
	v_max_f32_e32 v156, 0, v82
	v_add_f32_e32 v4, 1.0, v53
	v_exp_f32_e64 v53, -|v98|
	v_log_f32_e32 v158, v4
	v_max_f32_e32 v174, 0, v98
	v_add_f32_e32 v4, 1.0, v53
	v_exp_f32_e64 v53, -|v83|
	v_log_f32_e32 v176, v4
	v_max_f32_e32 v157, 0, v83
	v_add_f32_e32 v4, 1.0, v53
	v_log_f32_e32 v159, v4
	v_exp_f32_e64 v4, -|v99|
	v_max_f32_e32 v53, v99, v99
	v_add_f32_e32 v4, 1.0, v4
	v_log_f32_e32 v177, v4
	v_max_f32_e32 v2, 0, v68
	v_max_f32_e32 v3, 0, v69
	v_max_f32_e32 v175, 0, v53
	v_cndmask_b32_e64 v4, 0, 1, s[2:3]
	v_pk_add_f32 v[56:57], v[2:3], v[6:7]
	v_pk_add_f32 v[58:59], v[8:9], v[10:11]
	v_pk_add_f32 v[60:61], v[60:61], v[62:63]
	v_pk_add_f32 v[62:63], v[100:101], v[102:103]
	v_pk_add_f32 v[2:3], v[108:109], v[110:111]
	v_pk_add_f32 v[6:7], v[140:141], v[142:143]
	v_pk_add_f32 v[8:9], v[144:145], v[146:147]
	v_pk_add_f32 v[10:11], v[156:157], v[158:159]
	v_pk_add_f32 v[140:141], v[12:13], v[14:15]
	v_pk_add_f32 v[142:143], v[16:17], v[54:55]
	v_pk_add_f32 v[144:145], v[64:65], v[66:67]
	v_pk_add_f32 v[146:147], v[104:105], v[106:107]
	v_pk_add_f32 v[14:15], v[112:113], v[114:115]
	v_pk_add_f32 v[16:17], v[148:149], v[150:151]
	v_pk_add_f32 v[12:13], v[152:153], v[154:155]
	v_cmp_ne_u32_e64 s[74:75], 1, v4
	s_andn2_b64 vcc, exec, s[2:3]
	v_pk_add_f32 v[148:149], v[174:175], v[176:177]
	s_cbranch_vccnz .LBB0_950
; __device__ __forceinline__ int crow(int r, int hi) { return (r & 3) + 8 * (r >> 2) + 4 * hi; }
; template <bool NEED_SUM>
; __device__ __forceinline__ void sb_part1(SbTile& t, float& tsum, lds_cptr kslot, const bf16x8 (&qr)[4], bool masked, int qlim, int r32, int hi) {
;     ...
;     if (masked) {
;         asm volatile("; masked tile" ::: "memory");
; #pragma unroll
;         for (int r = 0; r < 16; ++r) { const int kv = crow(r, hi); if (kv >= qlim) l0[r] = 0.f; if (kv + 32 >= qlim) l1[r] = 0.f; }
;     }
	s_or_b64 vcc, s[68:69], s[64:65]
	v_cndmask_b32_e32 v10, 0, v10, vcc
	s_or_b64 vcc, vcc, s[60:61]
	v_cndmask_b32_e32 v9, 0, v9, vcc
	s_or_b64 vcc, vcc, s[56:57]
	v_cndmask_b32_e32 v8, 0, v8, vcc
	s_or_b64 vcc, vcc, s[52:53]
	v_cndmask_b32_e32 v7, 0, v7, vcc
	s_or_b64 vcc, vcc, s[48:49]
	v_cndmask_b32_e32 v6, 0, v6, vcc
	s_or_b64 vcc, vcc, s[44:45]
	v_cndmask_b32_e32 v3, 0, v3, vcc
	s_or_b64 vcc, vcc, s[40:41]
	v_cndmask_b32_e32 v2, 0, v2, vcc
	s_or_b64 vcc, vcc, s[36:37]
	v_cndmask_b32_e32 v63, 0, v63, vcc
	s_or_b64 vcc, vcc, s[30:31]
	v_cndmask_b32_e32 v62, 0, v62, vcc
	s_or_b64 vcc, vcc, s[26:27]
	v_cndmask_b32_e32 v61, 0, v61, vcc
	s_or_b64 vcc, vcc, s[22:23]
	v_cndmask_b32_e32 v60, 0, v60, vcc
	s_or_b64 vcc, vcc, s[18:19]
	v_cndmask_b32_e32 v59, 0, v59, vcc
	s_or_b64 vcc, vcc, s[14:15]
	v_cndmask_b32_e32 v58, 0, v58, vcc
	s_or_b64 vcc, vcc, s[10:11]
	v_cndmask_b32_e32 v57, 0, v57, vcc
	s_or_b64 vcc, vcc, s[6:7]
	v_cndmask_b32_e32 v56, 0, v56, vcc
	s_or_b64 vcc, s[70:71], s[66:67]
	v_cndmask_b32_e32 v148, 0, v148, vcc
	s_or_b64 vcc, vcc, s[62:63]
	v_cndmask_b32_e32 v13, 0, v13, vcc
	s_or_b64 vcc, vcc, s[58:59]
	v_cndmask_b32_e32 v12, 0, v12, vcc
	s_or_b64 vcc, vcc, s[54:55]
	v_cndmask_b32_e32 v17, 0, v17, vcc
	s_or_b64 vcc, vcc, s[50:51]
	v_cndmask_b32_e32 v16, 0, v16, vcc
	s_or_b64 vcc, vcc, s[46:47]
	v_cndmask_b32_e32 v15, 0, v15, vcc
	s_or_b64 vcc, vcc, s[42:43]
	v_cndmask_b32_e32 v14, 0, v14, vcc
	s_or_b64 vcc, vcc, s[38:39]
	v_cndmask_b32_e32 v147, 0, v147, vcc
	s_or_b64 vcc, vcc, s[34:35]
	v_cndmask_b32_e32 v146, 0, v146, vcc
	s_or_b64 vcc, vcc, s[28:29]
	v_cndmask_b32_e32 v145, 0, v145, vcc
	s_or_b64 vcc, vcc, s[24:25]
	v_cndmask_b32_e32 v144, 0, v144, vcc
	s_or_b64 vcc, vcc, s[20:21]
	v_cndmask_b32_e32 v143, 0, v143, vcc
	s_or_b64 vcc, vcc, s[16:17]
	v_cndmask_b32_e32 v142, 0, v142, vcc
	s_or_b64 vcc, vcc, s[12:13]
	v_cndmask_b32_e32 v141, 0, v141, vcc
	s_or_b64 vcc, vcc, s[8:9]
	v_cndmask_b32_e64 v11, 0, v11, s[68:69]
	v_cndmask_b32_e64 v149, 0, v149, s[70:71]
	v_cndmask_b32_e32 v140, 0, v140, vcc

; #define LAS __attribute__((address_space(3)))
; __device__ __forceinline__ int crow(int r, int hi) { return (r & 3) + 8 * (r >> 2) + 4 * hi; }
;     bf16x8 kf[8]; kfrags(kf, kslot, r32, hi);
;     f32x16 p0, p1;
; #pragma unroll
;     for (int g = 0; g < 4; ++g) { const f32x4 c0 = ld4(ckt + 8 * g), c1 = ld4(ckt + 32 + 8 * g);
; #pragma unroll
;         for (int i = 0; i < 4; ++i) { p0[4 * g + i] = c0[i]; p1[4 * g + i] = c1[i]; } }
;     u32x4 kn = {0u, 0xBF800000u, 0xBF80BF80u, 0u}; if (hi) { kn.y = 0u; kn.z = 0u; }
;     const bf16x8 kneg = __builtin_bit_cast(bf16x8, kn);
;     p0 = __builtin_amdgcn_mfma_f32_32x32x16_bf16(kneg, st.mq, p0, 0, 0, 0);
;     p1 = __builtin_amdgcn_mfma_f32_32x32x16_bf16(kneg, st.mq, p1, 0, 0, 0);
; #pragma unroll
;     for (int d0 = 0; d0 < 4; ++d0) {
;         p0 = __builtin_amdgcn_mfma_f32_32x32x16_bf16(kf[2 * d0], qr[d0], p0, 0, 0, 0);
;         p1 = __builtin_amdgcn_mfma_f32_32x32x16_bf16(kf[2 * d0 + 1], qr[d0], p1, 0, 0, 0);
;     }
;     __builtin_amdgcn_sched_barrier(0);
;     if (LEVEL == 2) { asm volatile("" :: "v"(p0), "v"(p1)); return; }
;     if (masked) {
;         asm volatile("; masked tile" ::: "memory");
; #pragma unroll
;         for (int r = 0; r < 16; ++r) { const int kv = crow(r, hi); if (kv >= qlim) p0[r] = NEG; if (kv + 32 >= qlim) p1[r] = NEG; }
;     }
; __device__ __forceinline__ void prompt_unit_fox(const Args& a, int l, int b, int h, int qb, LAS unsigned char* lds) {
;     ...
;         const lds_cptr kslot = (lds_cptr)lds + F_K + slot * 16384; const lds_cptr vp = vp0 + slot * 16384;
;         const LAS float* ck0 = (const LAS float*)(lds + F_CK) + (2 * jp) * 64 + 4 * hi;
;         if (pending) { fox_pair_pv(st, pp, vp0 + pslot * 16384); pending = false; }
;         if (jp < jpd) {
;             bool careful = false;
; #pragma unroll 1
;             for (int pass = 0; pass < 2; ++pass) { if (fox_pair_qs(st, pp, kslot, qr, (const LAS u32x2*)(lds + F_AUG) + (2 * jp) * 64 + r32, careful, r32, hi, wsf)) break; careful = true; }
;             if (lateB) { pending = true; pslot = slot; } else fox_pair_pv(st, pp, vp);
;         } else if (jp == jpd) {
;             if (jd & 1) { fox_tile(st, kslot + 8192, vp + 8192, qr, ck0 + 64, true, true, qlim, r32, hi, wsf); fox_tile(st, kslot, vp, qr, ck0, false, false, qlim, r32, hi, wsf); }
.LBB0_969:
	s_nop 9
	s_add_i32 s80, s33, 0
	s_lshl_b32 s81, s78, 7
	v_add_u32_e32 v190, s33, v175
	s_cmp_ge_i32 s78, s0
	s_mov_b64 s[2:3], -1
	s_cbranch_scc0 .LBB0_980
	v_mov_b64_e32 v[66:67], v[50:51]
	v_mov_b64_e32 v[82:83], v[34:35]
	v_mov_b64_e32 v[162:163], v[158:159]
	s_cmp_lg_u32 s78, s0
	v_mov_b64_e32 v[64:65], v[48:49]
	v_mov_b64_e32 v[62:63], v[46:47]
	v_mov_b64_e32 v[60:61], v[44:45]
	v_mov_b64_e32 v[58:59], v[42:43]
	v_mov_b64_e32 v[56:57], v[40:41]
	v_mov_b64_e32 v[54:55], v[38:39]
	v_mov_b64_e32 v[52:53], v[36:37]
	v_mov_b64_e32 v[80:81], v[32:33]
	v_mov_b64_e32 v[78:79], v[30:31]
	v_mov_b64_e32 v[76:77], v[28:29]
	v_mov_b64_e32 v[74:75], v[26:27]
	v_mov_b64_e32 v[72:73], v[24:25]
	v_mov_b64_e32 v[70:71], v[22:23]
	v_mov_b64_e32 v[68:69], v[20:21]
	v_mov_b64_e32 v[160:161], v[156:157]
	v_mov_b32_e32 v194, v192
	v_mov_b32_e32 v191, v193
	s_cbranch_scc1 .LBB0_979
	v_lshl_add_u32 v196, s81, 2, v186
	s_andn2_b64 vcc, exec, s[94:95]
	v_add3_u32 v195, s80, v182, v189
	s_cbranch_vccnz .LBB0_977
	ds_read_b128 v[68:71], v196 offset:256
	ds_read_b128 v[72:75], v196 offset:288
	ds_read_b128 v[76:79], v196 offset:320
	ds_read_b128 v[80:83], v196 offset:352
	ds_read_b128 v[52:55], v196 offset:384
	ds_read_b128 v[56:59], v196 offset:416
	ds_read_b128 v[60:63], v196 offset:448
	ds_read_b128 v[64:67], v196 offset:480
	ds_read_b128 v[84:87], v195 offset:8192
	s_waitcnt lgkmcnt(5)
	v_mfma_f32_32x32x16_bf16 v[68:83], v[120:123], v[156:159], v[68:83]
	s_waitcnt lgkmcnt(0)
	v_mfma_f32_32x32x16_bf16 v[68:83], v[84:87], v[6:9], v[68:83]
	ds_read_b128 v[84:87], v195 offset:8704
	v_mfma_f32_32x32x16_bf16 v[52:67], v[120:123], v[156:159], v[52:67]
	s_waitcnt lgkmcnt(0)
	v_mfma_f32_32x32x16_bf16 v[52:67], v[84:87], v[6:9], v[52:67]
	ds_read_b128 v[84:87], v195 offset:10240
	s_waitcnt lgkmcnt(0)
	v_mfma_f32_32x32x16_bf16 v[68:83], v[84:87], v[10:13], v[68:83]
	ds_read_b128 v[84:87], v195 offset:10752
	s_waitcnt lgkmcnt(0)
	v_mfma_f32_32x32x16_bf16 v[52:67], v[84:87], v[10:13], v[52:67]
	ds_read_b128 v[84:87], v195 offset:12288
	s_waitcnt lgkmcnt(0)
	v_mfma_f32_32x32x16_bf16 v[68:83], v[84:87], v[14:17], v[68:83]
	ds_read_b128 v[84:87], v195 offset:12800
	s_waitcnt lgkmcnt(0)
	v_mfma_f32_32x32x16_bf16 v[52:67], v[84:87], v[14:17], v[52:67]
	ds_read_b128 v[84:87], v195 offset:14336
	s_waitcnt lgkmcnt(0)
	v_mfma_f32_32x32x16_bf16 v[68:83], v[84:87], v[116:119], v[68:83]
	ds_read_b128 v[84:87], v195 offset:14848
	s_waitcnt lgkmcnt(0)
	v_mfma_f32_32x32x16_bf16 v[52:67], v[84:87], v[116:119], v[52:67]
	s_and_b64 vcc, s[70:71], s[66:67]
	s_nop 7
	v_cndmask_b32_e32 v82, v82, v18, vcc
	s_and_b64 vcc, vcc, s[62:63]
	v_cndmask_b32_e32 v81, v81, v18, vcc
	s_and_b64 vcc, vcc, s[58:59]
	v_cndmask_b32_e32 v80, v80, v18, vcc
	s_and_b64 vcc, vcc, s[54:55]
	v_cndmask_b32_e32 v79, v79, v18, vcc
	s_and_b64 vcc, vcc, s[50:51]
	v_cndmask_b32_e32 v78, v78, v18, vcc
	s_and_b64 vcc, vcc, s[46:47]
	v_cndmask_b32_e32 v77, v77, v18, vcc
	s_and_b64 vcc, vcc, s[42:43]
	v_cndmask_b32_e32 v76, v76, v18, vcc
	s_and_b64 vcc, vcc, s[38:39]
	v_cndmask_b32_e32 v75, v75, v18, vcc
	s_and_b64 vcc, vcc, s[34:35]
	v_cndmask_b32_e32 v74, v74, v18, vcc
	s_and_b64 vcc, vcc, s[28:29]
	v_cndmask_b32_e32 v73, v73, v18, vcc
	s_and_b64 vcc, vcc, s[24:25]
	v_cndmask_b32_e64 v3, v68, v18, s[8:9]
	v_cndmask_b32_e32 v72, v72, v18, vcc
	s_and_b64 vcc, vcc, s[20:21]
	v_cndmask_b32_e64 v3, v3, v68, s[12:13]
	v_cndmask_b32_e64 v4, v18, v69, s[12:13]
	v_cndmask_b32_e32 v71, v71, v18, vcc
	s_and_b64 vcc, vcc, s[16:17]
	v_cndmask_b32_e32 v69, v69, v4, vcc
	v_cndmask_b32_e32 v68, v68, v3, vcc
	v_cndmask_b32_e32 v70, v70, v18, vcc
	s_and_b64 vcc, s[72:73], s[68:69]
	v_cndmask_b32_e32 v66, v66, v18, vcc
	s_and_b64 vcc, vcc, s[64:65]
	v_cndmask_b32_e32 v65, v65, v18, vcc
	s_and_b64 vcc, vcc, s[60:61]
	v_cndmask_b32_e32 v64, v64, v18, vcc
	s_and_b64 vcc, vcc, s[56:57]
	v_cndmask_b32_e32 v63, v63, v18, vcc
	s_and_b64 vcc, vcc, s[52:53]
	v_cndmask_b32_e32 v62, v62, v18, vcc
	s_and_b64 vcc, vcc, s[48:49]
	v_cndmask_b32_e32 v61, v61, v18, vcc
	s_and_b64 vcc, vcc, s[44:45]
	v_cndmask_b32_e32 v60, v60, v18, vcc
	s_and_b64 vcc, vcc, s[40:41]
	v_cndmask_b32_e32 v59, v59, v18, vcc
	s_and_b64 vcc, vcc, s[36:37]
	v_cndmask_b32_e32 v58, v58, v18, vcc
	s_and_b64 vcc, vcc, s[30:31]
	v_cndmask_b32_e32 v57, v57, v18, vcc
	s_and_b64 vcc, vcc, s[26:27]
	v_cndmask_b32_e32 v56, v56, v18, vcc
	s_and_b64 vcc, vcc, s[22:23]
	v_cndmask_b32_e32 v55, v55, v18, vcc
	s_and_b64 vcc, vcc, s[18:19]
	v_cndmask_b32_e32 v54, v54, v18, vcc
	s_and_b64 vcc, vcc, s[14:15]
	v_cndmask_b32_e32 v53, v53, v18, vcc
	s_and_b64 vcc, vcc, s[10:11]
	v_cndmask_b32_e32 v52, v52, v18, vcc
	v_max_f32_e32 v3, v68, v68
	v_max_f32_e32 v4, v52, v52
	v_max_f32_e32 v3, v3, v4
	v_max3_f32 v4, v53, v70, v54
	v_max3_f32 v3, v3, v69, v71
	v_max3_f32 v4, v4, v72, v56
	v_max3_f32 v3, v3, v55, v73
	v_max3_f32 v4, v4, v74, v58
	v_max3_f32 v3, v3, v57, v75
	v_max3_f32 v4, v4, v76, v60
	v_max3_f32 v3, v3, v59, v77
	v_max3_f32 v4, v4, v78, v62
	v_max3_f32 v3, v3, v61, v79
	v_cndmask_b32_e64 v83, v83, v18, s[70:71]
	v_max3_f32 v4, v4, v80, v64
	v_max3_f32 v3, v3, v63, v81
	v_cndmask_b32_e64 v67, v67, v18, s[72:73]
	v_max3_f32 v4, v4, v82, v66
	v_max3_f32 v3, v3, v65, v83
	v_max3_f32 v3, v3, v67, v4
	v_mov_b32_e32 v4, v3
	s_nop 1
	v_permlane32_swap_b32_e32 v3, v4
	v_max_f32_e32 v4, v4, v4
	v_max_f32_e32 v3, v3, v3
	v_max_f32_e32 v84, v3, v4
	v_add_f32_e32 v191, v193, v84
	v_cvt_pk_bf16_f32 v3, v191, 0
	v_lshlrev_b32_e32 v3, 16, v3
	v_sub_f32_e32 v4, v191, v3
	v_cvt_pk_bf16_f32 v85, v4, 0
	v_lshlrev_b32_e32 v85, 16, v85
	v_sub_f32_e32 v4, v4, v85
	v_cvt_pk_bf16_f32 v3, 1.0, v3
; __device__ __forceinline__ unsigned cvtpk(float lo, float hi) { f32x2 v = {lo, hi}; bf16x2_t b = __builtin_convertvector(v, bf16x2_t); return __builtin_bit_cast(unsigned, b); }
; __device__ __forceinline__ float fadd_s(float a, float b) { float r = a + b; asm volatile("" : "+v"(r)); return r; }
; #define ATT_PACK4(P, B, F) (u32x4){F(P[B], P[B + 1]), F(P[B + 2], P[B + 3]), F(P[B + 4], P[B + 5]), F(P[B + 6], P[B + 7])}
;     bf16x8 kf[8]; kfrags(kf, kslot, r32, hi);
;     f32x16 p0, p1;
; #pragma unroll
;     for (int g = 0; g < 4; ++g) { const f32x4 c0 = ld4(ckt + 8 * g), c1 = ld4(ckt + 32 + 8 * g);
; #pragma unroll
;         for (int i = 0; i < 4; ++i) { p0[4 * g + i] = c0[i]; p1[4 * g + i] = c1[i]; } }
;     u32x4 kn = {0u, 0xBF800000u, 0xBF80BF80u, 0u}; if (hi) { kn.y = 0u; kn.z = 0u; }
;     const bf16x8 kneg = __builtin_bit_cast(bf16x8, kn);
;     p0 = __builtin_amdgcn_mfma_f32_32x32x16_bf16(kneg, st.mq, p0, 0, 0, 0);
;     p1 = __builtin_amdgcn_mfma_f32_32x32x16_bf16(kneg, st.mq, p1, 0, 0, 0);
; #pragma unroll
;     for (int d0 = 0; d0 < 4; ++d0) {
;         p0 = __builtin_amdgcn_mfma_f32_32x32x16_bf16(kf[2 * d0], qr[d0], p0, 0, 0, 0);
;         p1 = __builtin_amdgcn_mfma_f32_32x32x16_bf16(kf[2 * d0 + 1], qr[d0], p1, 0, 0, 0);
;     }
;     ...
;     VFrags vf; vfrags(vf, vp);
;     float sacc = 0.f, sacc2 = 0.f;
; #pragma unroll
;     for (int r = 0; r < 16; ++r) { p0[r] = __builtin_amdgcn_exp2f(p0[r]); p1[r] = __builtin_amdgcn_exp2f(p1[r]); sacc = fadd_s(sacc, p0[r]); sacc2 = fadd_s(sacc2, p1[r]); }
;     st.l = fadd_s(st.l, fadd_s(sacc, sacc2));
;     const u32x4 pw0 = ATT_PACK4(p0, 0, cvtpk), pw1 = ATT_PACK4(p0, 8, cvtpk), pw2 = ATT_PACK4(p1, 0, cvtpk), pw3 = ATT_PACK4(p1, 8, cvtpk);
;     __builtin_amdgcn_sched_barrier(0);
;     ...
;     pv(st.o, vf, pw0, pw1, pw2, pw3);
	v_cvt_pk_bf16_f32 v4, v85, v4
	v_cndmask_b32_e64 v4, 0, v4, s[6:7]
	v_cndmask_b32_e64 v3, 0, v3, s[6:7]
	v_sub_f32_e32 v68, v68, v84
	v_sub_f32_e32 v112, v52, v84
	v_sub_f32_e32 v69, v69, v84
	v_sub_f32_e32 v113, v53, v84
	v_sub_f32_e32 v70, v70, v84
	v_sub_f32_e32 v114, v54, v84
	v_sub_f32_e32 v71, v71, v84
	v_sub_f32_e32 v115, v55, v84
	v_sub_f32_e32 v72, v72, v84
	v_sub_f32_e32 v56, v56, v84
	v_sub_f32_e32 v73, v73, v84
	v_sub_f32_e32 v57, v57, v84
	v_sub_f32_e32 v74, v74, v84
	v_sub_f32_e32 v58, v58, v84
	v_sub_f32_e32 v75, v75, v84
	v_sub_f32_e32 v59, v59, v84
	v_sub_f32_e32 v76, v76, v84
	v_sub_f32_e32 v60, v60, v84
	v_sub_f32_e32 v77, v77, v84
	v_sub_f32_e32 v61, v61, v84
	v_sub_f32_e32 v78, v78, v84
	v_sub_f32_e32 v62, v62, v84
	v_sub_f32_e32 v79, v79, v84
	v_sub_f32_e32 v63, v63, v84
	v_sub_f32_e32 v80, v80, v84
	v_sub_f32_e32 v64, v64, v84
	v_sub_f32_e32 v81, v81, v84
	v_sub_f32_e32 v65, v65, v84
	v_sub_f32_e32 v82, v82, v84
	v_sub_f32_e32 v66, v66, v84
	v_sub_f32_e32 v83, v83, v84
	v_sub_f32_e32 v67, v67, v84
	v_exp_f32_e32 v68, v68
	v_exp_f32_e32 v164, v112
	v_exp_f32_e32 v69, v69
	v_exp_f32_e32 v165, v113
	v_add_f32_e32 v112, 0, v68
	v_exp_f32_e32 v70, v70
	ds_read_b64_tr_b16 v[52:53], v190 offset:57344
	ds_read_b64_tr_b16 v[54:55], v190 offset:57856
	ds_read_b64_tr_b16 v[84:85], v190 offset:58368
	ds_read_b64_tr_b16 v[86:87], v190 offset:58880
	ds_read_b64_tr_b16 v[88:89], v190 offset:59392
	ds_read_b64_tr_b16 v[90:91], v190 offset:59904
	ds_read_b64_tr_b16 v[92:93], v190 offset:60416
	ds_read_b64_tr_b16 v[94:95], v190 offset:60928
	ds_read_b64_tr_b16 v[96:97], v190 offset:61440
	ds_read_b64_tr_b16 v[98:99], v190 offset:61952
	ds_read_b64_tr_b16 v[100:101], v190 offset:62464
	ds_read_b64_tr_b16 v[102:103], v190 offset:62976
	ds_read_b64_tr_b16 v[104:105], v190 offset:63488
	ds_read_b64_tr_b16 v[106:107], v190 offset:64000
	ds_read_b64_tr_b16 v[108:109], v190 offset:64512
	ds_read_b64_tr_b16 v[110:111], v190 offset:65024
	v_exp_f32_e32 v166, v114
	v_add_f32_e32 v160, 0, v164
	v_add_f32_e32 v112, v112, v69
	v_exp_f32_e32 v71, v71
	v_exp_f32_e32 v167, v115
	v_add_f32_e32 v113, v160, v165
	v_add_f32_e32 v112, v112, v70
	v_exp_f32_e32 v72, v72
	v_add_f32_e32 v113, v113, v166
	v_exp_f32_e32 v56, v56
	v_add_f32_e32 v112, v112, v71
	v_exp_f32_e32 v73, v73
	v_add_f32_e32 v113, v113, v167
	v_exp_f32_e32 v57, v57
	v_add_f32_e32 v112, v112, v72
	v_exp_f32_e32 v74, v74
	v_add_f32_e32 v113, v113, v56
	v_exp_f32_e32 v58, v58
	v_add_f32_e32 v112, v112, v73
	v_exp_f32_e32 v75, v75
	v_add_f32_e32 v113, v113, v57
	v_exp_f32_e32 v59, v59
	v_add_f32_e32 v112, v112, v74
	v_exp_f32_e32 v76, v76
	v_add_f32_e32 v113, v113, v58
	v_exp_f32_e32 v60, v60
	v_add_f32_e32 v112, v112, v75
	v_exp_f32_e32 v77, v77
	v_add_f32_e32 v113, v113, v59
	v_exp_f32_e32 v61, v61
	v_add_f32_e32 v112, v76, v112
	v_exp_f32_e32 v78, v78
	v_add_f32_e32 v113, v60, v113
	v_exp_f32_e32 v62, v62
	v_add_f32_e32 v112, v77, v112
	v_exp_f32_e32 v79, v79
	v_add_f32_e32 v113, v61, v113
	v_exp_f32_e32 v63, v63
	v_add_f32_e32 v112, v78, v112
	v_exp_f32_e32 v80, v80
	v_add_f32_e32 v113, v62, v113
	v_exp_f32_e32 v64, v64
	v_add_f32_e32 v112, v79, v112
	v_exp_f32_e32 v81, v81
	v_add_f32_e32 v113, v63, v113
	v_exp_f32_e32 v65, v65
	v_add_f32_e32 v112, v80, v112
	v_exp_f32_e32 v82, v82
	v_add_f32_e32 v113, v64, v113
	v_exp_f32_e32 v66, v66
	v_add_f32_e32 v112, v81, v112
	v_exp_f32_e32 v83, v83
	v_add_f32_e32 v113, v65, v113
	v_exp_f32_e32 v67, v67
	v_add_f32_e32 v112, v82, v112
	v_add_f32_e32 v113, v66, v113
	v_add_f32_e32 v112, v83, v112
	v_add_f32_e32 v113, v67, v113
	v_cvt_pk_bf16_f32 v114, v72, v73
	v_add_f32_e32 v112, v112, v113
	v_cvt_pk_bf16_f32 v113, v70, v71
	v_add_f32_e32 v194, v192, v112
	v_cvt_pk_bf16_f32 v112, v68, v69
	v_cvt_pk_bf16_f32 v115, v74, v75
	v_cvt_pk_bf16_f32 v160, v76, v77
	v_cvt_pk_bf16_f32 v161, v78, v79
	v_cvt_pk_bf16_f32 v162, v80, v81
	v_cvt_pk_bf16_f32 v163, v82, v83
	v_cvt_pk_bf16_f32 v164, v164, v165
	v_cvt_pk_bf16_f32 v165, v166, v167
	v_cvt_pk_bf16_f32 v166, v56, v57
	v_cvt_pk_bf16_f32 v167, v58, v59
	v_cvt_pk_bf16_f32 v198, v60, v61
	v_cvt_pk_bf16_f32 v199, v62, v63
	v_cvt_pk_bf16_f32 v200, v64, v65
	v_cvt_pk_bf16_f32 v201, v66, v67
	s_waitcnt lgkmcnt(14)
	v_mfma_f32_32x32x16_bf16 v[68:83], v[112:115], v[52:55], v[20:35]
	s_waitcnt lgkmcnt(6)
	v_mfma_f32_32x32x16_bf16 v[52:67], v[112:115], v[96:99], v[36:51]
	v_mfma_f32_32x32x16_bf16 v[68:83], v[160:163], v[84:87], v[68:83]
	s_waitcnt lgkmcnt(4)
	v_mfma_f32_32x32x16_bf16 v[52:67], v[160:163], v[100:103], v[52:67]
	v_mfma_f32_32x32x16_bf16 v[68:83], v[164:167], v[88:91], v[68:83]
	s_waitcnt lgkmcnt(2)
	v_mfma_f32_32x32x16_bf16 v[52:67], v[164:167], v[104:107], v[52:67]
	v_mfma_f32_32x32x16_bf16 v[68:83], v[198:201], v[92:95], v[68:83]
	ds_read_b128 v[84:87], v196
	ds_read_b128 v[88:91], v196 offset:32
	ds_read_b128 v[92:95], v196 offset:64
	ds_read_b128 v[96:99], v196 offset:96
	s_waitcnt lgkmcnt(4)
	v_mfma_f32_32x32x16_bf16 v[52:67], v[198:201], v[108:111], v[52:67]
	ds_read_b128 v[100:103], v196 offset:128
	ds_read_b128 v[104:107], v196 offset:160
	ds_read_b128 v[108:111], v196 offset:192
	ds_read_b128 v[112:115], v196 offset:224
	ds_read_b128 v[160:163], v195
	ds_read_b128 v[164:167], v195 offset:512
	s_waitcnt lgkmcnt(6)
; #define LAS __attribute__((address_space(3)))
; __device__ __forceinline__ int crow(int r, int hi) { return (r & 3) + 8 * (r >> 2) + 4 * hi; }
; __device__ __forceinline__ float max3f(float a, float b, float c) { return __builtin_fmaxf(__builtin_fmaxf(a, b), c); }
;     ...
;     for (int g = 0; g < 4; ++g) { const f32x4 c0 = ld4(ckt + 8 * g), c1 = ld4(ckt + 32 + 8 * g);
; #pragma unroll
;         for (int i = 0; i < 4; ++i) { p0[4 * g + i] = c0[i]; p1[4 * g + i] = c1[i]; } }
;     u32x4 kn = {0u, 0xBF800000u, 0xBF80BF80u, 0u}; if (hi) { kn.y = 0u; kn.z = 0u; }
;     const bf16x8 kneg = __builtin_bit_cast(bf16x8, kn);
;     p0 = __builtin_amdgcn_mfma_f32_32x32x16_bf16(kneg, st.mq, p0, 0, 0, 0);
;     p1 = __builtin_amdgcn_mfma_f32_32x32x16_bf16(kneg, st.mq, p1, 0, 0, 0);
; #pragma unroll
;     for (int d0 = 0; d0 < 4; ++d0) {
;         p0 = __builtin_amdgcn_mfma_f32_32x32x16_bf16(kf[2 * d0], qr[d0], p0, 0, 0, 0);
;         p1 = __builtin_amdgcn_mfma_f32_32x32x16_bf16(kf[2 * d0 + 1], qr[d0], p1, 0, 0, 0);
;     }
;     __builtin_amdgcn_sched_barrier(0);
;     if (LEVEL == 2) { asm volatile("" :: "v"(p0), "v"(p1)); return; }
;     if (masked) {
;         asm volatile("; masked tile" ::: "memory");
; #pragma unroll
;         for (int r = 0; r < 16; ++r) { const int kv = crow(r, hi); if (kv >= qlim) p0[r] = NEG; if (kv + 32 >= qlim) p1[r] = NEG; }
;     }
;     float rm = max3f(p0[0], p1[0], p0[1]), rm2 = max3f(p1[1], p0[2], p1[2]);
; #pragma unroll
;     for (int r = 3; r < 15; r += 2) { rm = max3f(rm, p0[r], p1[r]); rm2 = max3f(rm2, p0[r + 1], p1[r + 1]); }
;     rm = max3f(rm, p0[15], p1[15]); rm = swap_max(max3f(rm, rm2, rm2));
;     if (first || __any(rm > FOX_THR)) {
;         const float dl = first ? rm : fmaxf(rm, 0.f);
;         st.m += dl; st.mq = make_mq(st.m, hi);
; #pragma unroll
;         for (int r = 0; r < 16; ++r) { p0[r] -= dl; p1[r] -= dl; }
;         if (!first) {
;             const float f = __builtin_amdgcn_exp2f(-dl);
;             st.l *= f;
;             if (hi == 0) wsf[r32] = f;
;             ATT_LDS_WAIT();
; #pragma unroll
;             for (int g = 0; g < 4; ++g) { const f32x4 fv = *(const LAS f32x4*)(wsf + 8 * g + 4 * hi);
; #pragma unroll
;                 for (int i = 0; i < 4; ++i) { st.o[0][4 * g + i] *= fv[i]; st.o[1][4 * g + i] *= fv[i]; } }
;         }
;     }
	v_mfma_f32_32x32x16_bf16 v[84:99], v[120:123], v[2:5], v[84:99]
	s_waitcnt lgkmcnt(2)
	v_mfma_f32_32x32x16_bf16 v[100:115], v[120:123], v[2:5], v[100:115]
	s_waitcnt lgkmcnt(1)
	v_mfma_f32_32x32x16_bf16 v[84:99], v[160:163], v[6:9], v[84:99]
	s_waitcnt lgkmcnt(0)
	v_mfma_f32_32x32x16_bf16 v[100:115], v[164:167], v[6:9], v[100:115]
	ds_read_b128 v[160:163], v195 offset:2048
	ds_read_b128 v[164:167], v195 offset:2560
	s_waitcnt lgkmcnt(1)
	v_mfma_f32_32x32x16_bf16 v[84:99], v[160:163], v[10:13], v[84:99]
	s_waitcnt lgkmcnt(0)
	v_mfma_f32_32x32x16_bf16 v[100:115], v[164:167], v[10:13], v[100:115]
	ds_read_b128 v[160:163], v195 offset:4096
	ds_read_b128 v[164:167], v195 offset:4608
	s_waitcnt lgkmcnt(1)
	v_mfma_f32_32x32x16_bf16 v[84:99], v[160:163], v[14:17], v[84:99]
	s_waitcnt lgkmcnt(0)
	v_mfma_f32_32x32x16_bf16 v[100:115], v[164:167], v[14:17], v[100:115]
	ds_read_b128 v[160:163], v195 offset:6144
	ds_read_b128 v[164:167], v195 offset:6656
	s_waitcnt lgkmcnt(1)
	v_mfma_f32_32x32x16_bf16 v[84:99], v[160:163], v[116:119], v[84:99]
	s_waitcnt lgkmcnt(0)
	v_mfma_f32_32x32x16_bf16 v[100:115], v[164:167], v[116:119], v[100:115]
	s_nop 11
	v_max_f32_e32 v160, v100, v100
	v_max_f32_e32 v161, v84, v84
	v_max_f32_e32 v160, v161, v160
	v_max3_f32 v161, v101, v86, v102
	v_max3_f32 v160, v160, v85, v87
	v_max3_f32 v161, v161, v88, v104
	v_max3_f32 v160, v160, v103, v89
	v_max3_f32 v161, v161, v90, v106
	v_max3_f32 v160, v160, v105, v91
	v_max3_f32 v161, v161, v92, v108
	v_max3_f32 v160, v160, v107, v93
	v_max3_f32 v161, v161, v94, v110
	v_max3_f32 v160, v160, v109, v95
	v_max3_f32 v161, v161, v96, v112
	v_max3_f32 v160, v160, v111, v97
	v_max3_f32 v161, v161, v98, v114
	v_max3_f32 v160, v160, v113, v99
	v_max3_f32 v160, v160, v115, v161
	v_mov_b32_e32 v161, v160
	s_nop 1
	v_permlane32_swap_b32_e32 v160, v161
	v_max_f32_e32 v161, v161, v161
	v_max_f32_e32 v160, v160, v160
	v_max_f32_e32 v160, v160, v161
	s_mov_b32 s2, 0x41000000
	v_cmp_lt_f32_e32 vcc, s2, v160
	s_cbranch_vccz .LBB0_976
	v_max_f32_e32 v160, 0, v160
	v_exp_f32_e64 v161, -v160
	s_and_saveexec_b64 s[2:3], s[6:7]
	ds_write_b32 v184, v161
	s_or_b64 exec, exec, s[2:3]
	v_add_f32_e32 v191, v191, v160
	v_cvt_pk_bf16_f32 v3, v191, 0
	v_lshlrev_b32_e32 v3, 16, v3
	v_sub_f32_e32 v4, v191, v3
	v_cvt_pk_bf16_f32 v162, v4, 0
	v_lshlrev_b32_e32 v162, 16, v162
	v_sub_f32_e32 v4, v4, v162
	s_waitcnt lgkmcnt(0)
	v_add_u32_e32 v197, s89, v174
	v_cvt_pk_bf16_f32 v4, v162, v4
	v_pk_add_f32 v[84:85], v[84:85], v[160:161] op_sel_hi:[1,0] neg_lo:[0,1] neg_hi:[0,1]
	v_pk_add_f32 v[100:101], v[100:101], v[160:161] op_sel_hi:[1,0] neg_lo:[0,1] neg_hi:[0,1]
	v_pk_add_f32 v[86:87], v[86:87], v[160:161] op_sel_hi:[1,0] neg_lo:[0,1] neg_hi:[0,1]
	v_pk_add_f32 v[102:103], v[102:103], v[160:161] op_sel_hi:[1,0] neg_lo:[0,1] neg_hi:[0,1]
	v_pk_add_f32 v[88:89], v[88:89], v[160:161] op_sel_hi:[1,0] neg_lo:[0,1] neg_hi:[0,1]
	v_pk_add_f32 v[104:105], v[104:105], v[160:161] op_sel_hi:[1,0] neg_lo:[0,1] neg_hi:[0,1]
	v_pk_add_f32 v[90:91], v[90:91], v[160:161] op_sel_hi:[1,0] neg_lo:[0,1] neg_hi:[0,1]
	v_pk_add_f32 v[106:107], v[106:107], v[160:161] op_sel_hi:[1,0] neg_lo:[0,1] neg_hi:[0,1]
	v_pk_add_f32 v[92:93], v[92:93], v[160:161] op_sel_hi:[1,0] neg_lo:[0,1] neg_hi:[0,1]
	v_pk_add_f32 v[108:109], v[108:109], v[160:161] op_sel_hi:[1,0] neg_lo:[0,1] neg_hi:[0,1]
	v_pk_add_f32 v[94:95], v[94:95], v[160:161] op_sel_hi:[1,0] neg_lo:[0,1] neg_hi:[0,1]
	v_pk_add_f32 v[110:111], v[110:111], v[160:161] op_sel_hi:[1,0] neg_lo:[0,1] neg_hi:[0,1]
	v_pk_add_f32 v[96:97], v[96:97], v[160:161] op_sel_hi:[1,0] neg_lo:[0,1] neg_hi:[0,1]
	v_pk_add_f32 v[112:113], v[112:113], v[160:161] op_sel_hi:[1,0] neg_lo:[0,1] neg_hi:[0,1]
	v_pk_add_f32 v[98:99], v[98:99], v[160:161] op_sel_hi:[1,0] neg_lo:[0,1] neg_hi:[0,1]
	v_pk_add_f32 v[114:115], v[114:115], v[160:161] op_sel_hi:[1,0] neg_lo:[0,1] neg_hi:[0,1]
	v_mul_f32_e32 v194, v194, v161
	ds_read_b128 v[160:163], v197
	ds_read_b128 v[164:167], v197 offset:32
	ds_read_b128 v[198:201], v197 offset:64
	ds_read_b128 v[202:205], v197 offset:96
	v_cvt_pk_bf16_f32 v3, 1.0, v3
	v_cndmask_b32_e64 v4, 0, v4, s[6:7]
	v_cndmask_b32_e64 v3, 0, v3, s[6:7]
	s_waitcnt lgkmcnt(1)
	v_pk_mul_f32 v[76:77], v[76:77], v[198:199]
	s_waitcnt lgkmcnt(0)
	v_pk_mul_f32 v[80:81], v[80:81], v[202:203]
	v_pk_mul_f32 v[72:73], v[72:73], v[164:165]
	v_pk_mul_f32 v[82:83], v[82:83], v[204:205]
	v_pk_mul_f32 v[78:79], v[78:79], v[200:201]
	v_pk_mul_f32 v[74:75], v[74:75], v[166:167]
	v_pk_mul_f32 v[70:71], v[70:71], v[162:163]
	v_pk_mul_f32 v[68:69], v[68:69], v[160:161]
	v_pk_mul_f32 v[64:65], v[64:65], v[202:203]
	v_pk_mul_f32 v[60:61], v[60:61], v[198:199]
	v_pk_mul_f32 v[56:57], v[56:57], v[164:165]
	v_pk_mul_f32 v[66:67], v[66:67], v[204:205]
	v_pk_mul_f32 v[62:63], v[62:63], v[200:201]
	v_pk_mul_f32 v[58:59], v[58:59], v[166:167]
	v_pk_mul_f32 v[54:55], v[54:55], v[162:163]
	v_pk_mul_f32 v[52:53], v[52:53], v[160:161]

; template <bool NEED_SUM>
; __device__ __forceinline__ void sb_part1(SbTile& t, float& tsum, lds_cptr kslot, const bf16x8 (&qr)[4], bool masked, int qlim, int r32, int hi) {
;     bf16x8 kf[8]; kfrags(kf, kslot, r32, hi);
;     t.z0 = (f32x16){}; t.z1 = (f32x16){};
; #pragma unroll
;     for (int d0 = 0; d0 < 4; ++d0) {
;         t.z0 = __builtin_amdgcn_mfma_f32_32x32x16_bf16(kf[2 * d0], qr[d0], t.z0, 0, 0, 0);
;         t.z1 = __builtin_amdgcn_mfma_f32_32x32x16_bf16(kf[2 * d0 + 1], qr[d0], t.z1, 0, 0, 0);
;     }
;     __builtin_amdgcn_sched_barrier(0);
;     f32x16 l0, l1;
; #pragma unroll
;     for (int r = 0; r < 16; ++r) {
;         const float a0 = t.z0[r], a1 = t.z1[r];
;         l0[r] = fmaxf(a0, 0.f) + __builtin_amdgcn_logf(1.0f + __builtin_amdgcn_exp2f(-__builtin_fabsf(a0)));
;         l1[r] = fmaxf(a1, 0.f) + __builtin_amdgcn_logf(1.0f + __builtin_amdgcn_exp2f(-__builtin_fabsf(a1)));
;     }
.LBB0_1077:
	s_or_b64 exec, exec, s[2:3]
	s_waitcnt vmcnt(0)
	v_cvt_pk_bf16_f32 v2, v10, v11
	v_cvt_pk_bf16_f32 v3, v12, v13
	v_cvt_pk_bf16_f32 v6, v6, v7
	v_cvt_pk_bf16_f32 v7, v8, v9
	v_add_u32_e32 v4, 0x2800, v236
	ds_write2_b64 v4, v[2:3], v[6:7] offset1:32
	v_cvt_pk_bf16_f32 v2, v52, v53
	v_cvt_pk_bf16_f32 v3, v54, v55
	v_cvt_pk_bf16_f32 v6, v14, v15
	v_cvt_pk_bf16_f32 v7, v16, v17
	ds_write2_b64 v4, v[2:3], v[6:7] offset0:64 offset1:96
	v_cvt_pk_bf16_f32 v2, v60, v61
	v_cvt_pk_bf16_f32 v3, v62, v63
	v_cvt_pk_bf16_f32 v6, v56, v57
	v_cvt_pk_bf16_f32 v7, v58, v59
	ds_write2_b64 v4, v[2:3], v[6:7] offset0:128 offset1:160
	v_cvt_pk_bf16_f32 v2, v68, v69
	v_cvt_pk_bf16_f32 v3, v70, v71
	v_cvt_pk_bf16_f32 v6, v64, v65
	v_cvt_pk_bf16_f32 v7, v66, v67
	ds_write2_b64 v4, v[2:3], v[6:7] offset0:192 offset1:224
	s_waitcnt lgkmcnt(0)
	ds_read_b128 v[6:9], v233
	s_waitcnt lgkmcnt(0)
	v_mfma_f32_32x32x16_bf16 v[52:67], v[6:9], v[124:127], 0
	ds_read_b128 v[6:9], v233 offset:512
	s_waitcnt lgkmcnt(0)
	v_mfma_f32_32x32x16_bf16 v[68:83], v[6:9], v[124:127], 0
	ds_read_b128 v[6:9], v233 offset:2048
	s_waitcnt lgkmcnt(0)
	v_mfma_f32_32x32x16_bf16 v[52:67], v[6:9], v[128:131], v[52:67]
	ds_read_b128 v[6:9], v233 offset:2560
	s_waitcnt lgkmcnt(0)
	v_mfma_f32_32x32x16_bf16 v[68:83], v[6:9], v[128:131], v[68:83]
	ds_read_b128 v[6:9], v233 offset:4096
	s_waitcnt lgkmcnt(0)
	v_mfma_f32_32x32x16_bf16 v[52:67], v[6:9], v[132:135], v[52:67]
	ds_read_b128 v[6:9], v233 offset:4608
	s_waitcnt lgkmcnt(0)
	v_mfma_f32_32x32x16_bf16 v[68:83], v[6:9], v[132:135], v[68:83]
	ds_read_b128 v[6:9], v233 offset:6144
	s_waitcnt lgkmcnt(0)
	v_mfma_f32_32x32x16_bf16 v[52:67], v[6:9], v[136:139], v[52:67]
	ds_read_b128 v[6:9], v233 offset:6656
	s_waitcnt lgkmcnt(0)
	v_mfma_f32_32x32x16_bf16 v[68:83], v[6:9], v[136:139], v[68:83]
	s_nop 8
	v_exp_f32_e64 v4, -|v53|
	v_exp_f32_e64 v9, -|v54|
	v_exp_f32_e64 v11, -|v55|
	v_exp_f32_e64 v13, -|v56|
	v_add_f32_e32 v4, 1.0, v4
	v_log_f32_e32 v7, v4
	v_max_f32_e32 v8, 0, v54
	v_add_f32_e32 v4, 1.0, v9
	v_log_f32_e32 v10, v4
	v_max_f32_e32 v9, 0, v55
	v_add_f32_e32 v4, 1.0, v11
	v_exp_f32_e64 v15, -|v57|
	v_log_f32_e32 v11, v4
	v_max_f32_e32 v12, 0, v56
	v_add_f32_e32 v4, 1.0, v13
	v_exp_f32_e64 v17, -|v58|
	v_log_f32_e32 v14, v4
	v_max_f32_e32 v13, 0, v57
	v_add_f32_e32 v4, 1.0, v15
	v_exp_f32_e64 v85, -|v59|
	v_log_f32_e32 v15, v4
	v_max_f32_e32 v16, 0, v58
	v_add_f32_e32 v4, 1.0, v17
	v_exp_f32_e64 v87, -|v60|
	v_log_f32_e32 v84, v4
	v_max_f32_e32 v17, 0, v59
	v_add_f32_e32 v4, 1.0, v85
	v_exp_f32_e64 v89, -|v61|
	v_log_f32_e32 v85, v4
	v_max_f32_e32 v86, 0, v60
	v_add_f32_e32 v4, 1.0, v87
	v_exp_f32_e64 v91, -|v62|
	v_log_f32_e32 v88, v4
	v_max_f32_e32 v87, 0, v61
	v_add_f32_e32 v4, 1.0, v89
	v_exp_f32_e64 v93, -|v63|
	v_log_f32_e32 v89, v4
	v_max_f32_e32 v90, 0, v62
	v_add_f32_e32 v4, 1.0, v91
	v_exp_f32_e64 v95, -|v64|
	v_log_f32_e32 v92, v4
	v_max_f32_e32 v91, 0, v63
	v_add_f32_e32 v4, 1.0, v93
	v_exp_f32_e64 v97, -|v65|
	v_log_f32_e32 v93, v4
	v_max_f32_e32 v94, 0, v64
	v_add_f32_e32 v4, 1.0, v95
	v_exp_f32_e64 v99, -|v66|
	v_log_f32_e32 v96, v4
	v_exp_f32_e64 v3, -|v52|
	v_max_f32_e32 v95, 0, v65
	v_add_f32_e32 v4, 1.0, v97
	v_exp_f32_e64 v101, -|v67|
	v_log_f32_e32 v97, v4
	v_max_f32_e32 v98, 0, v66
	v_add_f32_e32 v4, 1.0, v99
	v_log_f32_e32 v100, v4
	v_add_f32_e32 v3, 1.0, v3
	v_max_f32_e32 v99, 0, v67
	v_add_f32_e32 v4, 1.0, v101
	v_log_f32_e32 v6, v3
	v_log_f32_e32 v101, v4
	v_max_f32_e32 v2, 0, v52
	v_max_f32_e32 v3, 0, v53
	v_pk_add_f32 v[2:3], v[2:3], v[6:7]
	v_pk_add_f32 v[8:9], v[8:9], v[10:11]
	v_pk_add_f32 v[10:11], v[12:13], v[14:15]
	v_pk_add_f32 v[12:13], v[16:17], v[84:85]
	v_pk_add_f32 v[14:15], v[86:87], v[88:89]
	v_pk_add_f32 v[16:17], v[90:91], v[92:93]
	v_pk_add_f32 v[84:85], v[94:95], v[96:97]
	v_pk_add_f32 v[86:87], v[98:99], v[100:101]
	s_and_b64 vcc, exec, s[68:69]
	s_cbranch_vccnz .LBB0_1080
	v_exp_f32_e64 v4, -|v68|
	v_exp_f32_e64 v89, -|v69|
	v_exp_f32_e64 v91, -|v70|
	v_exp_f32_e64 v93, -|v71|
	v_add_f32_e32 v4, 1.0, v4
	v_log_f32_e32 v88, v4
	v_max_f32_e32 v7, 0, v69
	v_add_f32_e32 v4, 1.0, v89
	v_log_f32_e32 v89, v4
	v_max_f32_e32 v90, 0, v70
	v_add_f32_e32 v4, 1.0, v91
	v_exp_f32_e64 v95, -|v72|
	v_log_f32_e32 v92, v4
	v_max_f32_e32 v91, 0, v71
	v_add_f32_e32 v4, 1.0, v93
	v_exp_f32_e64 v97, -|v73|
	v_log_f32_e32 v93, v4
	v_max_f32_e32 v94, 0, v72
	v_add_f32_e32 v4, 1.0, v95
	v_exp_f32_e64 v99, -|v74|
	v_log_f32_e32 v96, v4
	v_max_f32_e32 v95, 0, v73
	v_add_f32_e32 v4, 1.0, v97
	v_exp_f32_e64 v101, -|v75|
	v_log_f32_e32 v97, v4
	v_max_f32_e32 v98, 0, v74
	v_add_f32_e32 v4, 1.0, v99
	v_exp_f32_e64 v103, -|v76|
	v_log_f32_e32 v100, v4
	v_max_f32_e32 v99, 0, v75
	v_add_f32_e32 v4, 1.0, v101
	v_exp_f32_e64 v105, -|v77|
	v_log_f32_e32 v101, v4
	v_max_f32_e32 v102, 0, v76
	v_add_f32_e32 v4, 1.0, v103
	v_log_f32_e32 v106, v4
	v_max_f32_e32 v103, 0, v77
	v_add_f32_e32 v4, 1.0, v105
	v_exp_f32_e64 v105, -|v78|
	v_log_f32_e32 v107, v4
	v_max_f32_e32 v108, 0, v78
	v_add_f32_e32 v4, 1.0, v105
	v_exp_f32_e64 v105, -|v79|
	v_log_f32_e32 v110, v4
	v_max_f32_e32 v109, 0, v79
	v_add_f32_e32 v4, 1.0, v105
	v_exp_f32_e64 v105, -|v80|
	v_log_f32_e32 v111, v4
	v_max_f32_e32 v112, 0, v80
	v_add_f32_e32 v4, 1.0, v105
	v_exp_f32_e64 v105, -|v81|
	v_log_f32_e32 v114, v4
	v_max_f32_e32 v113, 0, v81
	v_add_f32_e32 v4, 1.0, v105
	v_exp_f32_e64 v105, -|v82|
	v_log_f32_e32 v115, v4
	v_max_f32_e32 v140, 0, v82
	v_add_f32_e32 v4, 1.0, v105
	v_exp_f32_e64 v105, -|v83|
	v_log_f32_e32 v142, v4
	v_max_f32_e32 v141, 0, v83
	v_add_f32_e32 v4, 1.0, v105
	v_log_f32_e32 v143, v4
	v_max_f32_e32 v6, 0, v68
	v_pk_add_f32 v[88:89], v[6:7], v[88:89]
	v_pk_add_f32 v[90:91], v[90:91], v[92:93]
	v_pk_add_f32 v[94:95], v[94:95], v[96:97]
	v_pk_add_f32 v[98:99], v[98:99], v[100:101]
	v_pk_add_f32 v[92:93], v[102:103], v[106:107]
	v_pk_add_f32 v[96:97], v[108:109], v[110:111]
	v_pk_add_f32 v[100:101], v[112:113], v[114:115]
	v_pk_add_f32 v[102:103], v[140:141], v[142:143]
	s_branch .LBB0_1081
